# in-proj q/k rope epilogue: one copy + v_permlane32_swap per value, exec-masked halves consume the swapped pair directly (no second copy / select)
# speedup vs baseline: 1.0037x; 1.0037x over previous
;     __device__ __forceinline__ void operator()(const f32x4 (&acc)[2][2][4][2], const pg8::Unit& u, int wr, int wc, int fr, int fq) const {
;     ...
;         if (pn <= 2 && !(pn == 2 && wc >= 2)) {
;             const bool isq = pn < 2;
;             const float qscale = isq ? 0.125f * 1.4426950408889634f : 1.0f;
;             const float* g = isq ? gq : gk;
;             bf16* dst; int pitch, hcol;
;             if (isq) { dst = Q; pitch = 512; hcol = (pn * 4 + wc) * 64; } else { dst = K; pitch = 128; hcol = wc * 64; }
;             f32x4 gv[2][2];
; #pragma unroll
;             for (int bj = 0; bj < 2; ++bj)
; #pragma unroll
;                 for (int n = 0; n < 2; ++n) gv[bj][n] = *(const f32x4*)(g + 32 * bj + 8 * fq + 4 * n);
;             const int fbase = 8 * (fq & 1);
;             const bool lowhalf = fq < 2;
; #pragma unroll
;             for (int ai = 0; ai < 2; ++ai)
; #pragma unroll
;                 for (int m = 0; m < 4; ++m) {
;                     const int rl = ai * 128 + wr * 64 + m * 16 + fr;
;                     const int row = pm * 256 + rl;
;                     float ss = 0.f;
; #pragma unroll
;                     for (int bj = 0; bj < 2; ++bj)
; #pragma unroll
;                         for (int n = 0; n < 2; ++n) { const f32x4 v = acc[ai][bj][m][n]; ss += (v[0] * v[0] + v[1] * v[1]) + (v[2] * v[2] + v[3] * v[3]); }
;                     ss = sum_fq(ss);
;                     const float rstd = __builtin_amdgcn_rsqf(ss * (1.0f / 64.0f) + EPS);
;                     const int sp = seq0 + rl;
; #pragma unroll
;                     for (int bj = 0; bj < 2; ++bj) {
;                         f32x4 y0 = acc[ai][bj][m][0] * (rstd * qscale) * gv[bj][0], y1 = acc[ai][bj][m][1] * (rstd * qscale) * gv[bj][1];
;                         if (!isctx) {
;                             const int pos = bj == 0 ? (sp >> 6) : (sp & 63);
;                             const f32x4 c0 = *(const f32x4*)(ropec + pos * 16 + fbase), c1 = *(const f32x4*)(ropec + pos * 16 + fbase + 4);
;                             const f32x4 s0 = *(const f32x4*)(ropes + pos * 16 + fbase), s1 = *(const f32x4*)(ropes + pos * 16 + fbase + 4);
;                             f32x4 p0, p1;
; #pragma unroll
;                             for (int j = 0; j < 4; ++j) { p0[j] = xor32(y0[j], lowhalf); p1[j] = xor32(y1[j], lowhalf); }
.LBB0_222:
	s_cmp_gt_i32 s94, 2
	s_cselect_b64 s[6:7], -1, 0
	s_and_b64 vcc, exec, s[6:7]
	s_cbranch_vccnz .LBB0_322
	s_cmp_eq_u32 s94, 2
	s_cselect_b64 s[16:17], -1, 0
	s_and_b64 s[6:7], s[16:17], s[66:67]
	s_andn2_b64 vcc, exec, s[6:7]
	s_mov_b64 s[6:7], -1
	s_cbranch_vccz .LBB0_322
	s_mul_hi_i32 s5, s72, 0x78787879
	s_lshr_b32 s6, s5, 31
	s_ashr_i32 s5, s5, 3
	s_add_i32 s5, s5, s6
	s_mul_i32 s5, s5, 17
	s_mov_b64 s[52:53], s[40:41]
	s_mov_b64 s[46:47], s[42:43]
	s_sub_i32 s22, s72, s5
	s_load_dwordx4 s[40:43], s[0:1], 0x58
	s_cmp_lg_u32 s22, 0
	s_cselect_b64 s[6:7], -1, 0
	s_lshl_b32 s5, s22, 8
	s_addk_i32 s5, 0xff00
	s_and_b64 s[20:21], s[16:17], exec
	s_waitcnt lgkmcnt(0)
	s_cselect_b32 s20, s42, s40
	s_cselect_b32 s21, s43, s41
	s_add_u32 s20, s20, s70
	s_addc_u32 s21, s21, s71
	v_lshlrev_b32_e32 v132, 2, v170
	global_load_dwordx4 v[140:143], v132, s[20:21]
	global_load_dwordx4 v[136:139], v132, s[20:21] offset:16
	global_load_dwordx4 v[128:131], v132, s[20:21] offset:144
	s_nop 0
	global_load_dwordx4 v[132:135], v132, s[20:21] offset:128
	v_mul_f32_e32 v144, v125, v125
	v_mul_f32_e32 v145, v127, v127
	v_mul_f32_e32 v146, v121, v121
	v_mul_f32_e32 v147, v123, v123
	v_mul_f32_e32 v148, v117, v117
	v_mul_f32_e32 v149, v119, v119
	v_fmac_f32_e32 v144, v124, v124
	v_fmac_f32_e32 v145, v126, v126
	v_fmac_f32_e32 v146, v120, v120
	v_fmac_f32_e32 v147, v122, v122
	v_mul_f32_e32 v150, v109, v109
	v_mul_f32_e32 v151, v111, v111
	v_fmac_f32_e32 v148, v116, v116
	v_fmac_f32_e32 v149, v118, v118
	v_add_f32_e32 v144, v144, v145
	v_add_f32_e32 v145, v146, v147
	v_fmac_f32_e32 v150, v108, v108
	v_fmac_f32_e32 v151, v110, v110
	v_add_f32_e32 v146, v148, v149
	v_add_f32_e32 v144, v144, v145
	v_add_f32_e32 v147, v150, v151
	v_add_f32_e32 v144, v144, v146
	v_add_f32_e32 v144, v144, v147
	v_mov_b32_e32 v145, v144
	s_nop 1
	v_permlane16_swap_b32_e32 v144, v145
	v_add_f32_e32 v144, v144, v145
	v_mov_b32_e32 v145, v144
	s_nop 1
	v_permlane32_swap_b32_e32 v144, v145
	v_add_f32_e32 v144, v144, v145
	v_fmamk_f32 v144, v144, 0x3c800000, v200
	v_rsq_f32_e32 v144, v144
	v_cndmask_b32_e64 v227, v212, 1.0, s[16:17]
	s_cmp_eq_u32 s22, 0
	v_mul_f32_e32 v186, v227, v144
	v_pk_mul_f32 v[144:145], v[124:125], v[186:187] op_sel_hi:[1,0]
	v_pk_mul_f32 v[146:147], v[126:127], v[186:187] op_sel_hi:[1,0]
	v_pk_mul_f32 v[148:149], v[120:121], v[186:187] op_sel_hi:[1,0]
	v_pk_mul_f32 v[150:151], v[122:123], v[186:187] op_sel_hi:[1,0]
	s_waitcnt vmcnt(0)
	v_pk_mul_f32 v[190:191], v[142:143], v[146:147]
	v_pk_mul_f32 v[196:197], v[140:141], v[144:145]
	v_pk_mul_f32 v[188:189], v[138:139], v[150:151]
	v_pk_mul_f32 v[194:195], v[136:137], v[148:149]
	s_cbranch_scc1 .LBB0_230
	v_add_u32_e32 v144, s5, v217
	v_ashrrev_i32_e32 v144, 2, v144
	v_and_b32_e32 v144, -16, v144
	v_ashrrev_i32_e32 v145, 31, v144
	v_lshlrev_b64 v[148:149], 2, v[144:145]
	v_lshl_add_u64 v[150:151], v[172:173], 0, v[148:149]
	v_lshl_add_u64 v[156:157], v[174:175], 0, v[148:149]
	global_load_dwordx4 v[144:147], v[150:151], off offset:16
	global_load_dwordx4 v[152:155], v[150:151], off
	s_nop 0
	global_load_dwordx4 v[148:151], v[156:157], off offset:16
	s_nop 0
	global_load_dwordx4 v[156:159], v[156:157], off
	v_mov_b32_e32 v198, v196
	v_mov_b32_e32 v228, v194
	v_mov_b32_e32 v199, v197
	v_mov_b32_e32 v229, v195
	v_mov_b32_e32 v192, v190
	v_mov_b32_e32 v184, v188
	v_mov_b32_e32 v193, v191
	v_mov_b32_e32 v185, v189
	v_permlane32_swap_b32_e32 v198, v196
	v_permlane32_swap_b32_e32 v228, v194
	v_permlane32_swap_b32_e32 v199, v197
	v_permlane32_swap_b32_e32 v229, v195
	v_permlane32_swap_b32_e32 v192, v190
	v_permlane32_swap_b32_e32 v184, v188
	v_permlane32_swap_b32_e32 v193, v191
	v_permlane32_swap_b32_e32 v185, v189
	s_waitcnt vmcnt(1)
	s_waitcnt vmcnt(0)
	s_and_saveexec_b64 s[20:21], s[10:11]
	s_xor_b64 s[26:27], exec, s[20:21]
	v_pk_mul_f32 v[148:149], v[148:149], v[228:229]
	v_pk_mul_f32 v[156:157], v[156:157], v[198:199]
	v_pk_mul_f32 v[158:159], v[158:159], v[192:193]
	v_pk_mul_f32 v[150:151], v[150:151], v[184:185]
	v_pk_fma_f32 v[190:191], v[190:191], v[154:155], v[158:159]
	v_pk_fma_f32 v[196:197], v[196:197], v[152:153], v[156:157]
	v_pk_fma_f32 v[188:189], v[188:189], v[146:147], v[150:151]
	v_pk_fma_f32 v[194:195], v[194:195], v[144:145], v[148:149]
	s_or_saveexec_b64 s[26:27], s[26:27]
	s_mov_b64 s[42:43], s[46:47]
	s_mov_b64 s[40:41], s[52:53]
	s_xor_b64 exec, exec, s[26:27]
	v_pk_mul_f32 v[148:149], v[148:149], v[194:195]
	v_pk_mul_f32 v[156:157], v[156:157], v[196:197]
	v_pk_mul_f32 v[158:159], v[158:159], v[190:191]
	v_pk_mul_f32 v[150:151], v[150:151], v[188:189]
	v_pk_fma_f32 v[190:191], v[192:193], v[154:155], v[158:159] neg_lo:[0,0,1] neg_hi:[0,0,1]
	v_pk_fma_f32 v[196:197], v[198:199], v[152:153], v[156:157] neg_lo:[0,0,1] neg_hi:[0,0,1]
	v_pk_fma_f32 v[188:189], v[184:185], v[146:147], v[150:151] neg_lo:[0,0,1] neg_hi:[0,0,1]
	v_pk_fma_f32 v[194:195], v[228:229], v[144:145], v[148:149] neg_lo:[0,0,1] neg_hi:[0,0,1]
	s_or_b64 exec, exec, s[26:27]
	s_branch .LBB0_231

; __device__ __forceinline__ unsigned pk2(float lo, float hi) { return pg8::cvt_pk_bf16(lo, hi); }
;     __device__ __forceinline__ void operator()(const f32x4 (&acc)[2][2][4][2], const pg8::Unit& u, int wr, int wc, int fr, int fq) const {
;     ...
; #pragma unroll
;                     for (int bj = 0; bj < 2; ++bj)
; #pragma unroll
;                         for (int n = 0; n < 2; ++n) { const f32x4 v = acc[ai][bj][m][n]; ss += (v[0] * v[0] + v[1] * v[1]) + (v[2] * v[2] + v[3] * v[3]); }
;                     ss = sum_fq(ss);
;                     const float rstd = __builtin_amdgcn_rsqf(ss * (1.0f / 64.0f) + EPS);
;                     const int sp = seq0 + rl;
; #pragma unroll
;                     for (int bj = 0; bj < 2; ++bj) {
;                         f32x4 y0 = acc[ai][bj][m][0] * (rstd * qscale) * gv[bj][0], y1 = acc[ai][bj][m][1] * (rstd * qscale) * gv[bj][1];
;                         if (!isctx) {
;                             const int pos = bj == 0 ? (sp >> 6) : (sp & 63);
;                             const f32x4 c0 = *(const f32x4*)(ropec + pos * 16 + fbase), c1 = *(const f32x4*)(ropec + pos * 16 + fbase + 4);
;                             const f32x4 s0 = *(const f32x4*)(ropes + pos * 16 + fbase), s1 = *(const f32x4*)(ropes + pos * 16 + fbase + 4);
;                             f32x4 p0, p1;
; #pragma unroll
;                             for (int j = 0; j < 4; ++j) { p0[j] = xor32(y0[j], lowhalf); p1[j] = xor32(y1[j], lowhalf); }
;                             if (lowhalf) { y0 = y0 * c0 - p0 * s0; y1 = y1 * c1 - p1 * s1; }
;                             else         { y0 = p0 * s0 + y0 * c0; y1 = p1 * s1 + y1 * c1; }
;                         }
;                         u32x4 w; w.x = pk2(y0[0], y0[1]); w.y = pk2(y0[2], y0[3]); w.z = pk2(y1[0], y1[1]); w.w = pk2(y1[2], y1[3]);
;                         *(u32x4*)(dst + (size_t)row * pitch + hcol + 32 * bj + 8 * fq) = w;
.LBB0_231:
	s_lshl_b32 s22, s94, 8
	s_and_b64 s[20:21], s[16:17], exec
	s_cselect_b32 s20, 0, s22
	s_or_b32 s20, s20, s81
	s_and_b64 s[22:23], s[16:17], exec
	s_mov_b32 s21, 0x10dfa000
	s_cselect_b32 s21, s21, 0xebfa000
	s_lshl_b32 s26, s72, 8
	s_add_u32 s22, s28, s21
	s_addc_u32 s23, s29, 0
	s_and_b64 s[16:17], s[16:17], exec
	s_cselect_b32 s27, 7, 9
	s_ashr_i32 s21, s20, 31
	s_lshl_b64 s[16:17], s[20:21], 1
	s_add_u32 s16, s22, s16
	v_add_u32_e32 v144, s26, v217
	s_addc_u32 s17, s23, s17
	v_lshlrev_b32_e32 v160, 1, v170
	v_ashrrev_i32_e32 v145, 31, v144
	v_lshl_add_u64 v[184:185], s[16:17], 0, v[160:161]
	v_lshlrev_b64 v[144:145], s27, v[144:145]
	v_lshl_add_u64 v[192:193], v[144:145], 1, v[184:185]
	v_cvt_pk_bf16_f32 v144, v196, v197
	v_cvt_pk_bf16_f32 v145, v190, v191
	v_cvt_pk_bf16_f32 v146, v194, v195
	v_cvt_pk_bf16_f32 v147, v188, v189
	global_store_dwordx4 v[192:193], v[144:147], off
	v_mov_b32_e32 v187, v186
	v_pk_mul_f32 v[148:149], v[116:117], v[186:187]
	v_mov_b32_e32 v144, v186
	v_mov_b32_e32 v145, v186
	v_pk_mul_f32 v[146:147], v[118:119], v[144:145]
	v_pk_mul_f32 v[144:145], v[110:111], v[144:145]
	v_pk_mul_f32 v[188:189], v[134:135], v[146:147]
	v_pk_mul_f32 v[146:147], v[108:109], v[186:187]
	v_pk_mul_f32 v[190:191], v[132:133], v[148:149]
	v_pk_mul_f32 v[186:187], v[128:129], v[146:147]
	v_cndmask_b32_e64 v146, 0, 1, s[6:7]
	v_cmp_ne_u32_e64 s[16:17], 1, v146
	s_andn2_b64 vcc, exec, s[6:7]
	v_pk_mul_f32 v[194:195], v[130:131], v[144:145]
	s_cbranch_vccnz .LBB0_237
	global_load_dwordx4 v[144:147], v[176:177], off offset:16
	global_load_dwordx4 v[152:155], v[176:177], off
	global_load_dwordx4 v[148:151], v[178:179], off offset:16
	global_load_dwordx4 v[156:159], v[178:179], off
	v_mov_b32_e32 v228, v190
	v_mov_b32_e32 v230, v186
	v_mov_b32_e32 v229, v191
	v_mov_b32_e32 v231, v187
	v_mov_b32_e32 v198, v188
	v_mov_b32_e32 v196, v194
	v_mov_b32_e32 v199, v189
	v_mov_b32_e32 v197, v195
	v_permlane32_swap_b32_e32 v228, v190
	v_permlane32_swap_b32_e32 v230, v186
	v_permlane32_swap_b32_e32 v229, v191
	v_permlane32_swap_b32_e32 v231, v187
	v_permlane32_swap_b32_e32 v198, v188
	v_permlane32_swap_b32_e32 v196, v194
	v_permlane32_swap_b32_e32 v199, v189
	v_permlane32_swap_b32_e32 v197, v195
	s_waitcnt vmcnt(1)
	s_waitcnt vmcnt(0)
	s_and_saveexec_b64 s[6:7], s[10:11]
	s_xor_b64 s[6:7], exec, s[6:7]
	v_pk_mul_f32 v[148:149], v[148:149], v[230:231]
	v_pk_mul_f32 v[156:157], v[156:157], v[228:229]
	v_pk_mul_f32 v[158:159], v[158:159], v[198:199]
	v_pk_mul_f32 v[150:151], v[150:151], v[196:197]
	v_pk_fma_f32 v[188:189], v[188:189], v[154:155], v[158:159]
	v_pk_fma_f32 v[190:191], v[190:191], v[152:153], v[156:157]
	v_pk_fma_f32 v[194:195], v[194:195], v[146:147], v[150:151]
	v_pk_fma_f32 v[186:187], v[186:187], v[144:145], v[148:149]
	s_andn2_saveexec_b64 s[6:7], s[6:7]
	v_pk_mul_f32 v[148:149], v[148:149], v[186:187]
	v_pk_mul_f32 v[156:157], v[156:157], v[190:191]
	v_pk_mul_f32 v[158:159], v[158:159], v[188:189]
	v_pk_mul_f32 v[150:151], v[150:151], v[194:195]
	v_pk_fma_f32 v[188:189], v[198:199], v[154:155], v[158:159] neg_lo:[0,0,1] neg_hi:[0,0,1]
	v_pk_fma_f32 v[190:191], v[228:229], v[152:153], v[156:157] neg_lo:[0,0,1] neg_hi:[0,0,1]
	v_pk_fma_f32 v[194:195], v[196:197], v[146:147], v[150:151] neg_lo:[0,0,1] neg_hi:[0,0,1]
	v_pk_fma_f32 v[186:187], v[230:231], v[144:145], v[148:149] neg_lo:[0,0,1] neg_hi:[0,0,1]
	s_or_b64 exec, exec, s[6:7]
.LBB0_237:
	v_cvt_pk_bf16_f32 v144, v190, v191
	v_cvt_pk_bf16_f32 v145, v188, v189
	v_cvt_pk_bf16_f32 v146, v186, v187
	v_cvt_pk_bf16_f32 v147, v194, v195
	global_store_dwordx4 v[192:193], v[144:147], off offset:64
	s_and_b64 vcc, exec, s[16:17]
	s_nop 0
	v_mul_f32_e32 v144, v113, v113
	v_mul_f32_e32 v145, v115, v115
	v_fmac_f32_e32 v144, v112, v112
	v_fmac_f32_e32 v145, v114, v114
	v_add_f32_e32 v144, v144, v145
	v_mul_f32_e32 v145, v105, v105
	v_mul_f32_e32 v146, v107, v107
	v_fmac_f32_e32 v145, v104, v104
	v_fmac_f32_e32 v146, v106, v106
	v_add_f32_e32 v145, v145, v146
	v_add_f32_e32 v144, v144, v145
	v_mul_f32_e32 v145, v101, v101
	v_mul_f32_e32 v146, v103, v103
	v_fmac_f32_e32 v145, v100, v100
	v_fmac_f32_e32 v146, v102, v102
	v_add_f32_e32 v145, v145, v146
	v_add_f32_e32 v144, v144, v145
	v_mul_f32_e32 v145, v93, v93
	v_mul_f32_e32 v146, v95, v95
	v_fmac_f32_e32 v145, v92, v92
	v_fmac_f32_e32 v146, v94, v94
	v_add_f32_e32 v145, v145, v146
	v_add_f32_e32 v144, v144, v145
	v_mov_b32_e32 v145, v144
	s_nop 1
	v_permlane16_swap_b32_e32 v144, v145
	v_add_f32_e32 v144, v144, v145
	v_mov_b32_e32 v145, v144
	s_nop 1
	v_permlane32_swap_b32_e32 v144, v145
	v_add_f32_e32 v144, v144, v145
	v_fmamk_f32 v144, v144, 0x3c800000, v200
	v_rsq_f32_e32 v144, v144
	s_nop 0
	v_mul_f32_e32 v186, v227, v144
	v_pk_mul_f32 v[144:145], v[112:113], v[186:187] op_sel_hi:[1,0]
	v_pk_mul_f32 v[146:147], v[114:115], v[186:187] op_sel_hi:[1,0]
	v_pk_mul_f32 v[192:193], v[140:141], v[144:145]
	v_pk_mul_f32 v[190:191], v[142:143], v[146:147]
	v_pk_mul_f32 v[144:145], v[104:105], v[186:187] op_sel_hi:[1,0]
	v_pk_mul_f32 v[146:147], v[106:107], v[186:187] op_sel_hi:[1,0]
	v_pk_mul_f32 v[196:197], v[136:137], v[144:145]
	v_pk_mul_f32 v[194:195], v[138:139], v[146:147]
	s_cbranch_vccnz .LBB0_243
; __device__ __forceinline__ unsigned pk2(float lo, float hi) { return pg8::cvt_pk_bf16(lo, hi); }
;     __device__ __forceinline__ void operator()(const f32x4 (&acc)[2][2][4][2], const pg8::Unit& u, int wr, int wc, int fr, int fq) const {
;     ...
;                     for (int bj = 0; bj < 2; ++bj) {
;                         f32x4 y0 = acc[ai][bj][m][0] * (rstd * qscale) * gv[bj][0], y1 = acc[ai][bj][m][1] * (rstd * qscale) * gv[bj][1];
;                         if (!isctx) {
;                             const int pos = bj == 0 ? (sp >> 6) : (sp & 63);
;                             const f32x4 c0 = *(const f32x4*)(ropec + pos * 16 + fbase), c1 = *(const f32x4*)(ropec + pos * 16 + fbase + 4);
;                             const f32x4 s0 = *(const f32x4*)(ropes + pos * 16 + fbase), s1 = *(const f32x4*)(ropes + pos * 16 + fbase + 4);
;                             f32x4 p0, p1;
; #pragma unroll
;                             for (int j = 0; j < 4; ++j) { p0[j] = xor32(y0[j], lowhalf); p1[j] = xor32(y1[j], lowhalf); }
;                             if (lowhalf) { y0 = y0 * c0 - p0 * s0; y1 = y1 * c1 - p1 * s1; }
;                             else         { y0 = p0 * s0 + y0 * c0; y1 = p1 * s1 + y1 * c1; }
;                         }
;                         u32x4 w; w.x = pk2(y0[0], y0[1]); w.y = pk2(y0[2], y0[3]); w.z = pk2(y1[0], y1[1]); w.w = pk2(y1[2], y1[3]);
;                         *(u32x4*)(dst + (size_t)row * pitch + hcol + 32 * bj + 8 * fq) = w;
	v_add_u32_e32 v144, s5, v219
	v_ashrrev_i32_e32 v144, 2, v144
	v_and_b32_e32 v144, -16, v144
	v_ashrrev_i32_e32 v145, 31, v144
	v_lshlrev_b64 v[148:149], 2, v[144:145]
	v_lshl_add_u64 v[150:151], v[172:173], 0, v[148:149]
	v_lshl_add_u64 v[156:157], v[174:175], 0, v[148:149]
	global_load_dwordx4 v[144:147], v[150:151], off offset:16
	global_load_dwordx4 v[152:155], v[150:151], off
	s_nop 0
	global_load_dwordx4 v[148:151], v[156:157], off offset:16
	s_nop 0
	global_load_dwordx4 v[156:159], v[156:157], off
	v_mov_b32_e32 v228, v192
	v_mov_b32_e32 v230, v196
	v_mov_b32_e32 v229, v193
	v_mov_b32_e32 v231, v197
	v_mov_b32_e32 v198, v190
	v_mov_b32_e32 v188, v194
	v_mov_b32_e32 v199, v191
	v_mov_b32_e32 v189, v195
	v_permlane32_swap_b32_e32 v228, v192
	v_permlane32_swap_b32_e32 v230, v196
	v_permlane32_swap_b32_e32 v229, v193
	v_permlane32_swap_b32_e32 v231, v197
	v_permlane32_swap_b32_e32 v198, v190
	v_permlane32_swap_b32_e32 v188, v194
	v_permlane32_swap_b32_e32 v199, v191
	v_permlane32_swap_b32_e32 v189, v195
	s_waitcnt vmcnt(1)
	s_waitcnt vmcnt(0)
	s_and_saveexec_b64 s[6:7], s[10:11]
	s_xor_b64 s[6:7], exec, s[6:7]
	v_pk_mul_f32 v[148:149], v[148:149], v[230:231]
	v_pk_mul_f32 v[156:157], v[156:157], v[228:229]
	v_pk_mul_f32 v[158:159], v[158:159], v[198:199]
	v_pk_mul_f32 v[150:151], v[150:151], v[188:189]
	v_pk_fma_f32 v[190:191], v[190:191], v[154:155], v[158:159]
	v_pk_fma_f32 v[192:193], v[192:193], v[152:153], v[156:157]
	v_pk_fma_f32 v[194:195], v[194:195], v[146:147], v[150:151]
	v_pk_fma_f32 v[196:197], v[196:197], v[144:145], v[148:149]
	s_andn2_saveexec_b64 s[6:7], s[6:7]
	v_pk_mul_f32 v[148:149], v[148:149], v[196:197]
	v_pk_mul_f32 v[156:157], v[156:157], v[192:193]
	v_pk_mul_f32 v[158:159], v[158:159], v[190:191]
	v_pk_mul_f32 v[150:151], v[150:151], v[194:195]
	v_pk_fma_f32 v[190:191], v[198:199], v[154:155], v[158:159] neg_lo:[0,0,1] neg_hi:[0,0,1]
	v_pk_fma_f32 v[192:193], v[228:229], v[152:153], v[156:157] neg_lo:[0,0,1] neg_hi:[0,0,1]
	v_pk_fma_f32 v[194:195], v[188:189], v[146:147], v[150:151] neg_lo:[0,0,1] neg_hi:[0,0,1]
	v_pk_fma_f32 v[196:197], v[230:231], v[144:145], v[148:149] neg_lo:[0,0,1] neg_hi:[0,0,1]
	s_or_b64 exec, exec, s[6:7]
.LBB0_243:
	v_add_u32_e32 v144, s26, v219
	v_ashrrev_i32_e32 v145, 31, v144
	v_lshlrev_b64 v[144:145], s27, v[144:145]
	v_lshl_add_u64 v[188:189], v[144:145], 1, v[184:185]
	v_cvt_pk_bf16_f32 v144, v192, v193
	v_cvt_pk_bf16_f32 v145, v190, v191
	v_cvt_pk_bf16_f32 v146, v196, v197
	v_cvt_pk_bf16_f32 v147, v194, v195
	global_store_dwordx4 v[188:189], v[144:147], off
	v_mov_b32_e32 v187, v186
	v_pk_mul_f32 v[148:149], v[100:101], v[186:187]
	v_mov_b32_e32 v144, v186
	v_mov_b32_e32 v145, v186
	v_pk_mul_f32 v[146:147], v[102:103], v[144:145]
	v_pk_mul_f32 v[144:145], v[94:95], v[144:145]
	v_pk_mul_f32 v[190:191], v[134:135], v[146:147]
	v_pk_mul_f32 v[146:147], v[92:93], v[186:187]
	v_pk_mul_f32 v[192:193], v[132:133], v[148:149]
	v_pk_mul_f32 v[186:187], v[130:131], v[144:145]
	s_and_b64 vcc, exec, s[16:17]
	v_pk_mul_f32 v[194:195], v[128:129], v[146:147]
	s_cbranch_vccnz .LBB0_249
	global_load_dwordx4 v[144:147], v[176:177], off offset:1040
	global_load_dwordx4 v[152:155], v[176:177], off offset:1024
	global_load_dwordx4 v[148:151], v[178:179], off offset:1040
	global_load_dwordx4 v[156:159], v[178:179], off offset:1024
	v_mov_b32_e32 v228, v192
	v_mov_b32_e32 v230, v194
	v_mov_b32_e32 v229, v193
	v_mov_b32_e32 v231, v195
	v_mov_b32_e32 v198, v190
	v_mov_b32_e32 v196, v186
	v_mov_b32_e32 v199, v191
	v_mov_b32_e32 v197, v187
	v_permlane32_swap_b32_e32 v228, v192
	v_permlane32_swap_b32_e32 v230, v194
	v_permlane32_swap_b32_e32 v229, v193
	v_permlane32_swap_b32_e32 v231, v195
	v_permlane32_swap_b32_e32 v198, v190
	v_permlane32_swap_b32_e32 v196, v186
	v_permlane32_swap_b32_e32 v199, v191
	v_permlane32_swap_b32_e32 v197, v187
	s_waitcnt vmcnt(1)
	s_waitcnt vmcnt(0)
	s_and_saveexec_b64 s[6:7], s[10:11]
	s_xor_b64 s[6:7], exec, s[6:7]
	v_pk_mul_f32 v[148:149], v[148:149], v[230:231]
	v_pk_mul_f32 v[156:157], v[156:157], v[228:229]
	v_pk_mul_f32 v[158:159], v[158:159], v[198:199]
	v_pk_mul_f32 v[150:151], v[150:151], v[196:197]
	v_pk_fma_f32 v[190:191], v[190:191], v[154:155], v[158:159]
	v_pk_fma_f32 v[192:193], v[192:193], v[152:153], v[156:157]
	v_pk_fma_f32 v[186:187], v[186:187], v[146:147], v[150:151]
	v_pk_fma_f32 v[194:195], v[194:195], v[144:145], v[148:149]
	s_andn2_saveexec_b64 s[6:7], s[6:7]
	v_pk_mul_f32 v[148:149], v[148:149], v[194:195]
	v_pk_mul_f32 v[156:157], v[156:157], v[192:193]
	v_pk_mul_f32 v[158:159], v[158:159], v[190:191]
	v_pk_mul_f32 v[150:151], v[150:151], v[186:187]
	v_pk_fma_f32 v[190:191], v[198:199], v[154:155], v[158:159] neg_lo:[0,0,1] neg_hi:[0,0,1]
	v_pk_fma_f32 v[192:193], v[228:229], v[152:153], v[156:157] neg_lo:[0,0,1] neg_hi:[0,0,1]
	v_pk_fma_f32 v[186:187], v[196:197], v[146:147], v[150:151] neg_lo:[0,0,1] neg_hi:[0,0,1]
	v_pk_fma_f32 v[194:195], v[230:231], v[144:145], v[148:149] neg_lo:[0,0,1] neg_hi:[0,0,1]
	s_or_b64 exec, exec, s[6:7]
; __device__ __forceinline__ unsigned pk2(float lo, float hi) { return pg8::cvt_pk_bf16(lo, hi); }
;     __device__ __forceinline__ void operator()(const f32x4 (&acc)[2][2][4][2], const pg8::Unit& u, int wr, int wc, int fr, int fq) const {
;     ...
;                         for (int n = 0; n < 2; ++n) { const f32x4 v = acc[ai][bj][m][n]; ss += (v[0] * v[0] + v[1] * v[1]) + (v[2] * v[2] + v[3] * v[3]); }
;                     ss = sum_fq(ss);
;                     const float rstd = __builtin_amdgcn_rsqf(ss * (1.0f / 64.0f) + EPS);
;                     const int sp = seq0 + rl;
; #pragma unroll
;                     for (int bj = 0; bj < 2; ++bj) {
;                         f32x4 y0 = acc[ai][bj][m][0] * (rstd * qscale) * gv[bj][0], y1 = acc[ai][bj][m][1] * (rstd * qscale) * gv[bj][1];
;                         if (!isctx) {
;                             const int pos = bj == 0 ? (sp >> 6) : (sp & 63);
;                             const f32x4 c0 = *(const f32x4*)(ropec + pos * 16 + fbase), c1 = *(const f32x4*)(ropec + pos * 16 + fbase + 4);
;                             const f32x4 s0 = *(const f32x4*)(ropes + pos * 16 + fbase), s1 = *(const f32x4*)(ropes + pos * 16 + fbase + 4);
;                             f32x4 p0, p1;
; #pragma unroll
;                             for (int j = 0; j < 4; ++j) { p0[j] = xor32(y0[j], lowhalf); p1[j] = xor32(y1[j], lowhalf); }
;                             if (lowhalf) { y0 = y0 * c0 - p0 * s0; y1 = y1 * c1 - p1 * s1; }
;                             else         { y0 = p0 * s0 + y0 * c0; y1 = p1 * s1 + y1 * c1; }
;                         }
;                         u32x4 w; w.x = pk2(y0[0], y0[1]); w.y = pk2(y0[2], y0[3]); w.z = pk2(y1[0], y1[1]); w.w = pk2(y1[2], y1[3]);
;                         *(u32x4*)(dst + (size_t)row * pitch + hcol + 32 * bj + 8 * fq) = w;
.LBB0_249:
	v_cvt_pk_bf16_f32 v144, v192, v193
	v_cvt_pk_bf16_f32 v145, v190, v191
	v_cvt_pk_bf16_f32 v146, v194, v195
	v_cvt_pk_bf16_f32 v147, v186, v187
	global_store_dwordx4 v[188:189], v[144:147], off offset:64
	s_and_b64 vcc, exec, s[16:17]
	s_nop 0
	v_mul_f32_e32 v144, v97, v97
	v_mul_f32_e32 v145, v99, v99
	v_fmac_f32_e32 v144, v96, v96
	v_fmac_f32_e32 v145, v98, v98
	v_add_f32_e32 v144, v144, v145
	v_mul_f32_e32 v145, v89, v89
	v_mul_f32_e32 v146, v91, v91
	v_fmac_f32_e32 v145, v88, v88
	v_fmac_f32_e32 v146, v90, v90
	v_add_f32_e32 v145, v145, v146
	v_add_f32_e32 v144, v144, v145
	v_mul_f32_e32 v145, v85, v85
	v_mul_f32_e32 v146, v87, v87
	v_fmac_f32_e32 v145, v84, v84
	v_fmac_f32_e32 v146, v86, v86
	v_add_f32_e32 v145, v145, v146
	v_add_f32_e32 v144, v144, v145
	v_mul_f32_e32 v145, v77, v77
	v_mul_f32_e32 v146, v79, v79
	v_fmac_f32_e32 v145, v76, v76
	v_fmac_f32_e32 v146, v78, v78
	v_add_f32_e32 v145, v145, v146
	v_add_f32_e32 v144, v144, v145
	v_mov_b32_e32 v145, v144
	s_nop 1
	v_permlane16_swap_b32_e32 v144, v145
	v_add_f32_e32 v144, v144, v145
	v_mov_b32_e32 v145, v144
	s_nop 1
	v_permlane32_swap_b32_e32 v144, v145
	v_add_f32_e32 v144, v144, v145
	v_fmamk_f32 v144, v144, 0x3c800000, v200
	v_rsq_f32_e32 v144, v144
	s_nop 0
	v_mul_f32_e32 v186, v227, v144
	v_pk_mul_f32 v[144:145], v[96:97], v[186:187] op_sel_hi:[1,0]
	v_pk_mul_f32 v[146:147], v[98:99], v[186:187] op_sel_hi:[1,0]
	v_pk_mul_f32 v[192:193], v[140:141], v[144:145]
	v_pk_mul_f32 v[190:191], v[142:143], v[146:147]
	v_pk_mul_f32 v[144:145], v[88:89], v[186:187] op_sel_hi:[1,0]
	v_pk_mul_f32 v[146:147], v[90:91], v[186:187] op_sel_hi:[1,0]
	v_pk_mul_f32 v[196:197], v[136:137], v[144:145]
	v_pk_mul_f32 v[194:195], v[138:139], v[146:147]
	s_cbranch_vccnz .LBB0_255
	v_add_u32_e32 v144, s5, v220
	v_ashrrev_i32_e32 v144, 2, v144
	v_and_b32_e32 v144, -16, v144
	v_ashrrev_i32_e32 v145, 31, v144
	v_lshlrev_b64 v[148:149], 2, v[144:145]
	v_lshl_add_u64 v[150:151], v[172:173], 0, v[148:149]
	v_lshl_add_u64 v[156:157], v[174:175], 0, v[148:149]
	global_load_dwordx4 v[144:147], v[150:151], off offset:16
	global_load_dwordx4 v[152:155], v[150:151], off
	s_nop 0
	global_load_dwordx4 v[148:151], v[156:157], off offset:16
	s_nop 0
	global_load_dwordx4 v[156:159], v[156:157], off
	v_mov_b32_e32 v228, v192
	v_mov_b32_e32 v230, v196
	v_mov_b32_e32 v229, v193
	v_mov_b32_e32 v231, v197
	v_mov_b32_e32 v198, v190
	v_mov_b32_e32 v188, v194
	v_mov_b32_e32 v199, v191
	v_mov_b32_e32 v189, v195
	v_permlane32_swap_b32_e32 v228, v192
	v_permlane32_swap_b32_e32 v230, v196
	v_permlane32_swap_b32_e32 v229, v193
	v_permlane32_swap_b32_e32 v231, v197
	v_permlane32_swap_b32_e32 v198, v190
	v_permlane32_swap_b32_e32 v188, v194
	v_permlane32_swap_b32_e32 v199, v191
	v_permlane32_swap_b32_e32 v189, v195
	s_waitcnt vmcnt(1)
	s_waitcnt vmcnt(0)
	s_and_saveexec_b64 s[6:7], s[10:11]
	s_xor_b64 s[6:7], exec, s[6:7]
	v_pk_mul_f32 v[148:149], v[148:149], v[230:231]
	v_pk_mul_f32 v[156:157], v[156:157], v[228:229]
	v_pk_mul_f32 v[158:159], v[158:159], v[198:199]
	v_pk_mul_f32 v[150:151], v[150:151], v[188:189]
	v_pk_fma_f32 v[190:191], v[190:191], v[154:155], v[158:159]
	v_pk_fma_f32 v[192:193], v[192:193], v[152:153], v[156:157]
	v_pk_fma_f32 v[194:195], v[194:195], v[146:147], v[150:151]
	v_pk_fma_f32 v[196:197], v[196:197], v[144:145], v[148:149]
	s_andn2_saveexec_b64 s[6:7], s[6:7]
	v_pk_mul_f32 v[148:149], v[148:149], v[196:197]
	v_pk_mul_f32 v[156:157], v[156:157], v[192:193]
	v_pk_mul_f32 v[158:159], v[158:159], v[190:191]
	v_pk_mul_f32 v[150:151], v[150:151], v[194:195]
	v_pk_fma_f32 v[190:191], v[198:199], v[154:155], v[158:159] neg_lo:[0,0,1] neg_hi:[0,0,1]
	v_pk_fma_f32 v[192:193], v[228:229], v[152:153], v[156:157] neg_lo:[0,0,1] neg_hi:[0,0,1]
	v_pk_fma_f32 v[194:195], v[188:189], v[146:147], v[150:151] neg_lo:[0,0,1] neg_hi:[0,0,1]
	v_pk_fma_f32 v[196:197], v[230:231], v[144:145], v[148:149] neg_lo:[0,0,1] neg_hi:[0,0,1]
	s_or_b64 exec, exec, s[6:7]
.LBB0_255:
	v_add_u32_e32 v144, s26, v220
	v_ashrrev_i32_e32 v145, 31, v144
	v_lshlrev_b64 v[144:145], s27, v[144:145]
	v_lshl_add_u64 v[188:189], v[144:145], 1, v[184:185]
	v_cvt_pk_bf16_f32 v144, v192, v193
	v_cvt_pk_bf16_f32 v145, v190, v191
	v_cvt_pk_bf16_f32 v146, v196, v197
	v_cvt_pk_bf16_f32 v147, v194, v195
	global_store_dwordx4 v[188:189], v[144:147], off
	v_mov_b32_e32 v187, v186
	v_pk_mul_f32 v[148:149], v[84:85], v[186:187]
	v_mov_b32_e32 v144, v186
	v_mov_b32_e32 v145, v186
	v_pk_mul_f32 v[146:147], v[86:87], v[144:145]
	v_pk_mul_f32 v[144:145], v[78:79], v[144:145]
	v_pk_mul_f32 v[190:191], v[134:135], v[146:147]
	v_pk_mul_f32 v[146:147], v[76:77], v[186:187]
	v_pk_mul_f32 v[192:193], v[132:133], v[148:149]
	v_pk_mul_f32 v[186:187], v[130:131], v[144:145]
	s_and_b64 vcc, exec, s[16:17]
	v_pk_mul_f32 v[194:195], v[128:129], v[146:147]
	s_cbranch_vccnz .LBB0_261
	global_load_dwordx4 v[144:147], v[176:177], off offset:2064
	global_load_dwordx4 v[152:155], v[176:177], off offset:2048
	global_load_dwordx4 v[148:151], v[178:179], off offset:2064
	global_load_dwordx4 v[156:159], v[178:179], off offset:2048
	v_mov_b32_e32 v228, v192
	v_mov_b32_e32 v230, v194
	v_mov_b32_e32 v229, v193
	v_mov_b32_e32 v231, v195
	v_mov_b32_e32 v198, v190
	v_mov_b32_e32 v196, v186
	v_mov_b32_e32 v199, v191
	v_mov_b32_e32 v197, v187
	v_permlane32_swap_b32_e32 v228, v192
	v_permlane32_swap_b32_e32 v230, v194
	v_permlane32_swap_b32_e32 v229, v193
	v_permlane32_swap_b32_e32 v231, v195
	v_permlane32_swap_b32_e32 v198, v190
	v_permlane32_swap_b32_e32 v196, v186
	v_permlane32_swap_b32_e32 v199, v191
	v_permlane32_swap_b32_e32 v197, v187
	s_waitcnt vmcnt(1)
	s_waitcnt vmcnt(0)
	s_and_saveexec_b64 s[6:7], s[10:11]
	s_xor_b64 s[6:7], exec, s[6:7]
	v_pk_mul_f32 v[148:149], v[148:149], v[230:231]
	v_pk_mul_f32 v[156:157], v[156:157], v[228:229]
	v_pk_mul_f32 v[158:159], v[158:159], v[198:199]
	v_pk_mul_f32 v[150:151], v[150:151], v[196:197]
	v_pk_fma_f32 v[190:191], v[190:191], v[154:155], v[158:159]
	v_pk_fma_f32 v[192:193], v[192:193], v[152:153], v[156:157]
	v_pk_fma_f32 v[186:187], v[186:187], v[146:147], v[150:151]
	v_pk_fma_f32 v[194:195], v[194:195], v[144:145], v[148:149]
	s_andn2_saveexec_b64 s[6:7], s[6:7]
	v_pk_mul_f32 v[148:149], v[148:149], v[194:195]
	v_pk_mul_f32 v[156:157], v[156:157], v[192:193]
	v_pk_mul_f32 v[158:159], v[158:159], v[190:191]
	v_pk_mul_f32 v[150:151], v[150:151], v[186:187]
	v_pk_fma_f32 v[190:191], v[198:199], v[154:155], v[158:159] neg_lo:[0,0,1] neg_hi:[0,0,1]
	v_pk_fma_f32 v[192:193], v[228:229], v[152:153], v[156:157] neg_lo:[0,0,1] neg_hi:[0,0,1]
	v_pk_fma_f32 v[186:187], v[196:197], v[146:147], v[150:151] neg_lo:[0,0,1] neg_hi:[0,0,1]
	v_pk_fma_f32 v[194:195], v[230:231], v[144:145], v[148:149] neg_lo:[0,0,1] neg_hi:[0,0,1]
	s_or_b64 exec, exec, s[6:7]
; __device__ __forceinline__ unsigned pk2(float lo, float hi) { return pg8::cvt_pk_bf16(lo, hi); }
;     __device__ __forceinline__ void operator()(const f32x4 (&acc)[2][2][4][2], const pg8::Unit& u, int wr, int wc, int fr, int fq) const {
;     ...
;                         for (int n = 0; n < 2; ++n) { const f32x4 v = acc[ai][bj][m][n]; ss += (v[0] * v[0] + v[1] * v[1]) + (v[2] * v[2] + v[3] * v[3]); }
;                     ss = sum_fq(ss);
;                     const float rstd = __builtin_amdgcn_rsqf(ss * (1.0f / 64.0f) + EPS);
;                     const int sp = seq0 + rl;
; #pragma unroll
;                     for (int bj = 0; bj < 2; ++bj) {
;                         f32x4 y0 = acc[ai][bj][m][0] * (rstd * qscale) * gv[bj][0], y1 = acc[ai][bj][m][1] * (rstd * qscale) * gv[bj][1];
;                         if (!isctx) {
;                             const int pos = bj == 0 ? (sp >> 6) : (sp & 63);
;                             const f32x4 c0 = *(const f32x4*)(ropec + pos * 16 + fbase), c1 = *(const f32x4*)(ropec + pos * 16 + fbase + 4);
;                             const f32x4 s0 = *(const f32x4*)(ropes + pos * 16 + fbase), s1 = *(const f32x4*)(ropes + pos * 16 + fbase + 4);
;                             f32x4 p0, p1;
; #pragma unroll
;                             for (int j = 0; j < 4; ++j) { p0[j] = xor32(y0[j], lowhalf); p1[j] = xor32(y1[j], lowhalf); }
;                             if (lowhalf) { y0 = y0 * c0 - p0 * s0; y1 = y1 * c1 - p1 * s1; }
;                             else         { y0 = p0 * s0 + y0 * c0; y1 = p1 * s1 + y1 * c1; }
;                         }
;                         u32x4 w; w.x = pk2(y0[0], y0[1]); w.y = pk2(y0[2], y0[3]); w.z = pk2(y1[0], y1[1]); w.w = pk2(y1[2], y1[3]);
;                         *(u32x4*)(dst + (size_t)row * pitch + hcol + 32 * bj + 8 * fq) = w;
.LBB0_261:
	v_cvt_pk_bf16_f32 v144, v192, v193
	v_cvt_pk_bf16_f32 v145, v190, v191
	v_cvt_pk_bf16_f32 v146, v194, v195
	v_cvt_pk_bf16_f32 v147, v186, v187
	global_store_dwordx4 v[188:189], v[144:147], off offset:64
	s_and_b64 vcc, exec, s[16:17]
	s_nop 0
	v_mul_f32_e32 v144, v81, v81
	v_mul_f32_e32 v145, v83, v83
	v_fmac_f32_e32 v144, v80, v80
	v_fmac_f32_e32 v145, v82, v82
	v_add_f32_e32 v144, v144, v145
	v_mul_f32_e32 v145, v73, v73
	v_mul_f32_e32 v146, v75, v75
	v_fmac_f32_e32 v145, v72, v72
	v_fmac_f32_e32 v146, v74, v74
	v_add_f32_e32 v145, v145, v146
	v_add_f32_e32 v144, v144, v145
	v_mul_f32_e32 v145, v69, v69
	v_mul_f32_e32 v146, v71, v71
	v_fmac_f32_e32 v145, v68, v68
	v_fmac_f32_e32 v146, v70, v70
	v_add_f32_e32 v145, v145, v146
	v_add_f32_e32 v144, v144, v145
	v_mul_f32_e32 v145, v65, v65
	v_mul_f32_e32 v146, v67, v67
	v_fmac_f32_e32 v145, v64, v64
	v_fmac_f32_e32 v146, v66, v66
	v_add_f32_e32 v145, v145, v146
	v_add_f32_e32 v144, v144, v145
	v_mov_b32_e32 v145, v144
	s_nop 1
	v_permlane16_swap_b32_e32 v144, v145
	v_add_f32_e32 v144, v144, v145
	v_mov_b32_e32 v145, v144
	s_nop 1
	v_permlane32_swap_b32_e32 v144, v145
	v_add_f32_e32 v144, v144, v145
	v_fmamk_f32 v144, v144, 0x3c800000, v200
	v_rsq_f32_e32 v144, v144
	s_nop 0
	v_mul_f32_e32 v186, v227, v144
	v_pk_mul_f32 v[144:145], v[80:81], v[186:187] op_sel_hi:[1,0]
	v_pk_mul_f32 v[146:147], v[82:83], v[186:187] op_sel_hi:[1,0]
	v_pk_mul_f32 v[192:193], v[140:141], v[144:145]
	v_pk_mul_f32 v[190:191], v[142:143], v[146:147]
	v_pk_mul_f32 v[144:145], v[72:73], v[186:187] op_sel_hi:[1,0]
	v_pk_mul_f32 v[146:147], v[74:75], v[186:187] op_sel_hi:[1,0]
	v_pk_mul_f32 v[196:197], v[136:137], v[144:145]
	v_pk_mul_f32 v[194:195], v[138:139], v[146:147]
	s_cbranch_vccnz .LBB0_267
	v_add_u32_e32 v144, s5, v221
	v_ashrrev_i32_e32 v144, 2, v144
	v_and_b32_e32 v144, -16, v144
	v_ashrrev_i32_e32 v145, 31, v144
	v_lshlrev_b64 v[148:149], 2, v[144:145]
	v_lshl_add_u64 v[150:151], v[172:173], 0, v[148:149]
	v_lshl_add_u64 v[156:157], v[174:175], 0, v[148:149]
	global_load_dwordx4 v[144:147], v[150:151], off offset:16
	global_load_dwordx4 v[152:155], v[150:151], off
	s_nop 0
	global_load_dwordx4 v[148:151], v[156:157], off offset:16
	s_nop 0
	global_load_dwordx4 v[156:159], v[156:157], off
	v_mov_b32_e32 v228, v192
	v_mov_b32_e32 v230, v196
	v_mov_b32_e32 v229, v193
	v_mov_b32_e32 v231, v197
	v_mov_b32_e32 v198, v190
	v_mov_b32_e32 v188, v194
	v_mov_b32_e32 v199, v191
	v_mov_b32_e32 v189, v195
	v_permlane32_swap_b32_e32 v228, v192
	v_permlane32_swap_b32_e32 v230, v196
	v_permlane32_swap_b32_e32 v229, v193
	v_permlane32_swap_b32_e32 v231, v197
	v_permlane32_swap_b32_e32 v198, v190
	v_permlane32_swap_b32_e32 v188, v194
	v_permlane32_swap_b32_e32 v199, v191
	v_permlane32_swap_b32_e32 v189, v195
	s_waitcnt vmcnt(1)
	s_waitcnt vmcnt(0)
	s_and_saveexec_b64 s[6:7], s[10:11]
	s_xor_b64 s[6:7], exec, s[6:7]
	v_pk_mul_f32 v[148:149], v[148:149], v[230:231]
	v_pk_mul_f32 v[156:157], v[156:157], v[228:229]
	v_pk_mul_f32 v[158:159], v[158:159], v[198:199]
	v_pk_mul_f32 v[150:151], v[150:151], v[188:189]
	v_pk_fma_f32 v[190:191], v[190:191], v[154:155], v[158:159]
	v_pk_fma_f32 v[192:193], v[192:193], v[152:153], v[156:157]
	v_pk_fma_f32 v[194:195], v[194:195], v[146:147], v[150:151]
	v_pk_fma_f32 v[196:197], v[196:197], v[144:145], v[148:149]
	s_andn2_saveexec_b64 s[6:7], s[6:7]
	v_pk_mul_f32 v[148:149], v[148:149], v[196:197]
	v_pk_mul_f32 v[156:157], v[156:157], v[192:193]
	v_pk_mul_f32 v[158:159], v[158:159], v[190:191]
	v_pk_mul_f32 v[150:151], v[150:151], v[194:195]
	v_pk_fma_f32 v[190:191], v[198:199], v[154:155], v[158:159] neg_lo:[0,0,1] neg_hi:[0,0,1]
	v_pk_fma_f32 v[192:193], v[228:229], v[152:153], v[156:157] neg_lo:[0,0,1] neg_hi:[0,0,1]
	v_pk_fma_f32 v[194:195], v[188:189], v[146:147], v[150:151] neg_lo:[0,0,1] neg_hi:[0,0,1]
	v_pk_fma_f32 v[196:197], v[230:231], v[144:145], v[148:149] neg_lo:[0,0,1] neg_hi:[0,0,1]
	s_or_b64 exec, exec, s[6:7]
.LBB0_267:
	v_add_u32_e32 v144, s26, v221
	v_ashrrev_i32_e32 v145, 31, v144
	v_lshlrev_b64 v[144:145], s27, v[144:145]
	v_lshl_add_u64 v[188:189], v[144:145], 1, v[184:185]
	v_cvt_pk_bf16_f32 v144, v192, v193
	v_cvt_pk_bf16_f32 v145, v190, v191
	v_cvt_pk_bf16_f32 v146, v196, v197
	v_cvt_pk_bf16_f32 v147, v194, v195
	global_store_dwordx4 v[188:189], v[144:147], off
	v_mov_b32_e32 v187, v186
	v_pk_mul_f32 v[148:149], v[68:69], v[186:187]
	v_mov_b32_e32 v144, v186
	v_mov_b32_e32 v145, v186
	v_pk_mul_f32 v[146:147], v[70:71], v[144:145]
	v_pk_mul_f32 v[144:145], v[66:67], v[144:145]
	v_pk_mul_f32 v[190:191], v[134:135], v[146:147]
	v_pk_mul_f32 v[146:147], v[64:65], v[186:187]
	v_pk_mul_f32 v[192:193], v[132:133], v[148:149]
	v_pk_mul_f32 v[186:187], v[130:131], v[144:145]
	s_and_b64 vcc, exec, s[16:17]
	v_pk_mul_f32 v[194:195], v[128:129], v[146:147]
	s_cbranch_vccnz .LBB0_273
	global_load_dwordx4 v[144:147], v[176:177], off offset:3088
	global_load_dwordx4 v[152:155], v[176:177], off offset:3072
	global_load_dwordx4 v[148:151], v[178:179], off offset:3088
	global_load_dwordx4 v[156:159], v[178:179], off offset:3072
	v_mov_b32_e32 v228, v192
	v_mov_b32_e32 v230, v194
	v_mov_b32_e32 v229, v193
	v_mov_b32_e32 v231, v195
	v_mov_b32_e32 v198, v190
	v_mov_b32_e32 v196, v186
	v_mov_b32_e32 v199, v191
	v_mov_b32_e32 v197, v187
	v_permlane32_swap_b32_e32 v228, v192
	v_permlane32_swap_b32_e32 v230, v194
	v_permlane32_swap_b32_e32 v229, v193
	v_permlane32_swap_b32_e32 v231, v195
	v_permlane32_swap_b32_e32 v198, v190
	v_permlane32_swap_b32_e32 v196, v186
	v_permlane32_swap_b32_e32 v199, v191
	v_permlane32_swap_b32_e32 v197, v187
	s_waitcnt vmcnt(1)
	s_waitcnt vmcnt(0)
	s_and_saveexec_b64 s[6:7], s[10:11]
	s_xor_b64 s[6:7], exec, s[6:7]
	v_pk_mul_f32 v[148:149], v[148:149], v[230:231]
	v_pk_mul_f32 v[156:157], v[156:157], v[228:229]
	v_pk_mul_f32 v[158:159], v[158:159], v[198:199]
	v_pk_mul_f32 v[150:151], v[150:151], v[196:197]
	v_pk_fma_f32 v[190:191], v[190:191], v[154:155], v[158:159]
	v_pk_fma_f32 v[192:193], v[192:193], v[152:153], v[156:157]
	v_pk_fma_f32 v[186:187], v[186:187], v[146:147], v[150:151]
	v_pk_fma_f32 v[194:195], v[194:195], v[144:145], v[148:149]
	s_andn2_saveexec_b64 s[6:7], s[6:7]
	v_pk_mul_f32 v[148:149], v[148:149], v[194:195]
	v_pk_mul_f32 v[156:157], v[156:157], v[192:193]
	v_pk_mul_f32 v[158:159], v[158:159], v[190:191]
	v_pk_mul_f32 v[150:151], v[150:151], v[186:187]
	v_pk_fma_f32 v[190:191], v[198:199], v[154:155], v[158:159] neg_lo:[0,0,1] neg_hi:[0,0,1]
	v_pk_fma_f32 v[192:193], v[228:229], v[152:153], v[156:157] neg_lo:[0,0,1] neg_hi:[0,0,1]
	v_pk_fma_f32 v[186:187], v[196:197], v[146:147], v[150:151] neg_lo:[0,0,1] neg_hi:[0,0,1]
	v_pk_fma_f32 v[194:195], v[230:231], v[144:145], v[148:149] neg_lo:[0,0,1] neg_hi:[0,0,1]
	s_or_b64 exec, exec, s[6:7]
; __device__ __forceinline__ unsigned pk2(float lo, float hi) { return pg8::cvt_pk_bf16(lo, hi); }
;     __device__ __forceinline__ void operator()(const f32x4 (&acc)[2][2][4][2], const pg8::Unit& u, int wr, int wc, int fr, int fq) const {
;     ...
;                         for (int n = 0; n < 2; ++n) { const f32x4 v = acc[ai][bj][m][n]; ss += (v[0] * v[0] + v[1] * v[1]) + (v[2] * v[2] + v[3] * v[3]); }
;                     ss = sum_fq(ss);
;                     const float rstd = __builtin_amdgcn_rsqf(ss * (1.0f / 64.0f) + EPS);
;                     const int sp = seq0 + rl;
; #pragma unroll
;                     for (int bj = 0; bj < 2; ++bj) {
;                         f32x4 y0 = acc[ai][bj][m][0] * (rstd * qscale) * gv[bj][0], y1 = acc[ai][bj][m][1] * (rstd * qscale) * gv[bj][1];
;                         if (!isctx) {
;                             const int pos = bj == 0 ? (sp >> 6) : (sp & 63);
;                             const f32x4 c0 = *(const f32x4*)(ropec + pos * 16 + fbase), c1 = *(const f32x4*)(ropec + pos * 16 + fbase + 4);
;                             const f32x4 s0 = *(const f32x4*)(ropes + pos * 16 + fbase), s1 = *(const f32x4*)(ropes + pos * 16 + fbase + 4);
;                             f32x4 p0, p1;
; #pragma unroll
;                             for (int j = 0; j < 4; ++j) { p0[j] = xor32(y0[j], lowhalf); p1[j] = xor32(y1[j], lowhalf); }
;                             if (lowhalf) { y0 = y0 * c0 - p0 * s0; y1 = y1 * c1 - p1 * s1; }
;                             else         { y0 = p0 * s0 + y0 * c0; y1 = p1 * s1 + y1 * c1; }
;                         }
;                         u32x4 w; w.x = pk2(y0[0], y0[1]); w.y = pk2(y0[2], y0[3]); w.z = pk2(y1[0], y1[1]); w.w = pk2(y1[2], y1[3]);
;                         *(u32x4*)(dst + (size_t)row * pitch + hcol + 32 * bj + 8 * fq) = w;
.LBB0_273:
	v_cvt_pk_bf16_f32 v144, v192, v193
	v_cvt_pk_bf16_f32 v145, v190, v191
	v_cvt_pk_bf16_f32 v146, v194, v195
	v_cvt_pk_bf16_f32 v147, v186, v187
	global_store_dwordx4 v[188:189], v[144:147], off offset:64
	s_and_b64 vcc, exec, s[16:17]
	s_nop 0
	v_mul_f32_e32 v144, v61, v61
	v_mul_f32_e32 v145, v63, v63
	v_fmac_f32_e32 v144, v60, v60
	v_fmac_f32_e32 v145, v62, v62
	v_add_f32_e32 v144, v144, v145
	v_mul_f32_e32 v145, v57, v57
	v_mul_f32_e32 v146, v59, v59
	v_fmac_f32_e32 v145, v56, v56
	v_fmac_f32_e32 v146, v58, v58
	v_add_f32_e32 v145, v145, v146
	v_add_f32_e32 v144, v144, v145
	v_mul_f32_e32 v145, v53, v53
	v_mul_f32_e32 v146, v55, v55
	v_fmac_f32_e32 v145, v52, v52
	v_fmac_f32_e32 v146, v54, v54
	v_add_f32_e32 v145, v145, v146
	v_add_f32_e32 v144, v144, v145
	v_mul_f32_e32 v145, v45, v45
	v_mul_f32_e32 v146, v47, v47
	v_fmac_f32_e32 v145, v44, v44
	v_fmac_f32_e32 v146, v46, v46
	v_add_f32_e32 v145, v145, v146
	v_add_f32_e32 v144, v144, v145
	v_mov_b32_e32 v145, v144
	s_nop 1
	v_permlane16_swap_b32_e32 v144, v145
	v_add_f32_e32 v144, v144, v145
	v_mov_b32_e32 v145, v144
	s_nop 1
	v_permlane32_swap_b32_e32 v144, v145
	v_add_f32_e32 v144, v144, v145
	v_fmamk_f32 v144, v144, 0x3c800000, v200
	v_rsq_f32_e32 v144, v144
	s_nop 0
	v_mul_f32_e32 v186, v227, v144
	v_pk_mul_f32 v[144:145], v[60:61], v[186:187] op_sel_hi:[1,0]
	v_pk_mul_f32 v[146:147], v[62:63], v[186:187] op_sel_hi:[1,0]
	v_pk_mul_f32 v[192:193], v[140:141], v[144:145]
	v_pk_mul_f32 v[190:191], v[142:143], v[146:147]
	v_pk_mul_f32 v[144:145], v[56:57], v[186:187] op_sel_hi:[1,0]
	v_pk_mul_f32 v[146:147], v[58:59], v[186:187] op_sel_hi:[1,0]
	v_pk_mul_f32 v[196:197], v[136:137], v[144:145]
	v_pk_mul_f32 v[194:195], v[138:139], v[146:147]
	s_cbranch_vccnz .LBB0_279
	v_add_u32_e32 v144, s5, v222
	v_ashrrev_i32_e32 v144, 2, v144
	v_and_b32_e32 v144, -16, v144
	v_ashrrev_i32_e32 v145, 31, v144
	v_lshlrev_b64 v[148:149], 2, v[144:145]
	v_lshl_add_u64 v[150:151], v[172:173], 0, v[148:149]
	v_lshl_add_u64 v[156:157], v[174:175], 0, v[148:149]
	global_load_dwordx4 v[144:147], v[150:151], off offset:16
	global_load_dwordx4 v[152:155], v[150:151], off
	s_nop 0
	global_load_dwordx4 v[148:151], v[156:157], off offset:16
	s_nop 0
	global_load_dwordx4 v[156:159], v[156:157], off
	v_mov_b32_e32 v228, v192
	v_mov_b32_e32 v230, v196
	v_mov_b32_e32 v229, v193
	v_mov_b32_e32 v231, v197
	v_mov_b32_e32 v198, v190
	v_mov_b32_e32 v188, v194
	v_mov_b32_e32 v199, v191
	v_mov_b32_e32 v189, v195
	v_permlane32_swap_b32_e32 v228, v192
	v_permlane32_swap_b32_e32 v230, v196
	v_permlane32_swap_b32_e32 v229, v193
	v_permlane32_swap_b32_e32 v231, v197
	v_permlane32_swap_b32_e32 v198, v190
	v_permlane32_swap_b32_e32 v188, v194
	v_permlane32_swap_b32_e32 v199, v191
	v_permlane32_swap_b32_e32 v189, v195
	s_waitcnt vmcnt(1)
	s_waitcnt vmcnt(0)
	s_and_saveexec_b64 s[6:7], s[10:11]
	s_xor_b64 s[6:7], exec, s[6:7]
	v_pk_mul_f32 v[148:149], v[148:149], v[230:231]
	v_pk_mul_f32 v[156:157], v[156:157], v[228:229]
	v_pk_mul_f32 v[158:159], v[158:159], v[198:199]
	v_pk_mul_f32 v[150:151], v[150:151], v[188:189]
	v_pk_fma_f32 v[190:191], v[190:191], v[154:155], v[158:159]
	v_pk_fma_f32 v[192:193], v[192:193], v[152:153], v[156:157]
	v_pk_fma_f32 v[194:195], v[194:195], v[146:147], v[150:151]
	v_pk_fma_f32 v[196:197], v[196:197], v[144:145], v[148:149]
	s_andn2_saveexec_b64 s[6:7], s[6:7]
	v_pk_mul_f32 v[148:149], v[148:149], v[196:197]
	v_pk_mul_f32 v[156:157], v[156:157], v[192:193]
	v_pk_mul_f32 v[158:159], v[158:159], v[190:191]
	v_pk_mul_f32 v[150:151], v[150:151], v[194:195]
	v_pk_fma_f32 v[190:191], v[198:199], v[154:155], v[158:159] neg_lo:[0,0,1] neg_hi:[0,0,1]
	v_pk_fma_f32 v[192:193], v[228:229], v[152:153], v[156:157] neg_lo:[0,0,1] neg_hi:[0,0,1]
	v_pk_fma_f32 v[194:195], v[188:189], v[146:147], v[150:151] neg_lo:[0,0,1] neg_hi:[0,0,1]
	v_pk_fma_f32 v[196:197], v[230:231], v[144:145], v[148:149] neg_lo:[0,0,1] neg_hi:[0,0,1]
	s_or_b64 exec, exec, s[6:7]
.LBB0_279:
	v_add_u32_e32 v144, s26, v222
	v_ashrrev_i32_e32 v145, 31, v144
	v_lshlrev_b64 v[144:145], s27, v[144:145]
	v_lshl_add_u64 v[188:189], v[144:145], 1, v[184:185]
	v_cvt_pk_bf16_f32 v144, v192, v193
	v_cvt_pk_bf16_f32 v145, v190, v191
	v_cvt_pk_bf16_f32 v146, v196, v197
	v_cvt_pk_bf16_f32 v147, v194, v195
	global_store_dwordx4 v[188:189], v[144:147], off
	v_mov_b32_e32 v187, v186
	v_pk_mul_f32 v[148:149], v[52:53], v[186:187]
	v_mov_b32_e32 v144, v186
	v_mov_b32_e32 v145, v186
	v_pk_mul_f32 v[146:147], v[54:55], v[144:145]
	v_pk_mul_f32 v[144:145], v[46:47], v[144:145]
	v_pk_mul_f32 v[190:191], v[134:135], v[146:147]
	v_pk_mul_f32 v[146:147], v[44:45], v[186:187]
	v_pk_mul_f32 v[192:193], v[132:133], v[148:149]
	v_pk_mul_f32 v[186:187], v[130:131], v[144:145]
	s_and_b64 vcc, exec, s[16:17]
	v_pk_mul_f32 v[194:195], v[128:129], v[146:147]
	s_cbranch_vccnz .LBB0_285
	global_load_dwordx4 v[144:147], v[176:177], off offset:16
	global_load_dwordx4 v[152:155], v[176:177], off
	global_load_dwordx4 v[148:151], v[178:179], off offset:16
	global_load_dwordx4 v[156:159], v[178:179], off
	v_mov_b32_e32 v228, v192
	v_mov_b32_e32 v230, v194
	v_mov_b32_e32 v229, v193
	v_mov_b32_e32 v231, v195
	v_mov_b32_e32 v198, v190
	v_mov_b32_e32 v196, v186
	v_mov_b32_e32 v199, v191
	v_mov_b32_e32 v197, v187
	v_permlane32_swap_b32_e32 v228, v192
	v_permlane32_swap_b32_e32 v230, v194
	v_permlane32_swap_b32_e32 v229, v193
	v_permlane32_swap_b32_e32 v231, v195
	v_permlane32_swap_b32_e32 v198, v190
	v_permlane32_swap_b32_e32 v196, v186
	v_permlane32_swap_b32_e32 v199, v191
	v_permlane32_swap_b32_e32 v197, v187
	s_waitcnt vmcnt(1)
	s_waitcnt vmcnt(0)
	s_and_saveexec_b64 s[6:7], s[10:11]
	s_xor_b64 s[6:7], exec, s[6:7]
	v_pk_mul_f32 v[148:149], v[148:149], v[230:231]
	v_pk_mul_f32 v[156:157], v[156:157], v[228:229]
	v_pk_mul_f32 v[158:159], v[158:159], v[198:199]
	v_pk_mul_f32 v[150:151], v[150:151], v[196:197]
	v_pk_fma_f32 v[190:191], v[190:191], v[154:155], v[158:159]
	v_pk_fma_f32 v[192:193], v[192:193], v[152:153], v[156:157]
	v_pk_fma_f32 v[186:187], v[186:187], v[146:147], v[150:151]
	v_pk_fma_f32 v[194:195], v[194:195], v[144:145], v[148:149]
	s_andn2_saveexec_b64 s[6:7], s[6:7]
	v_pk_mul_f32 v[148:149], v[148:149], v[194:195]
	v_pk_mul_f32 v[156:157], v[156:157], v[192:193]
	v_pk_mul_f32 v[158:159], v[158:159], v[190:191]
	v_pk_mul_f32 v[150:151], v[150:151], v[186:187]
	v_pk_fma_f32 v[190:191], v[198:199], v[154:155], v[158:159] neg_lo:[0,0,1] neg_hi:[0,0,1]
	v_pk_fma_f32 v[192:193], v[228:229], v[152:153], v[156:157] neg_lo:[0,0,1] neg_hi:[0,0,1]
	v_pk_fma_f32 v[186:187], v[196:197], v[146:147], v[150:151] neg_lo:[0,0,1] neg_hi:[0,0,1]
	v_pk_fma_f32 v[194:195], v[230:231], v[144:145], v[148:149] neg_lo:[0,0,1] neg_hi:[0,0,1]
	s_or_b64 exec, exec, s[6:7]
; __device__ __forceinline__ unsigned pk2(float lo, float hi) { return pg8::cvt_pk_bf16(lo, hi); }
;     __device__ __forceinline__ void operator()(const f32x4 (&acc)[2][2][4][2], const pg8::Unit& u, int wr, int wc, int fr, int fq) const {
;     ...
;                         for (int n = 0; n < 2; ++n) { const f32x4 v = acc[ai][bj][m][n]; ss += (v[0] * v[0] + v[1] * v[1]) + (v[2] * v[2] + v[3] * v[3]); }
;                     ss = sum_fq(ss);
;                     const float rstd = __builtin_amdgcn_rsqf(ss * (1.0f / 64.0f) + EPS);
;                     const int sp = seq0 + rl;
; #pragma unroll
;                     for (int bj = 0; bj < 2; ++bj) {
;                         f32x4 y0 = acc[ai][bj][m][0] * (rstd * qscale) * gv[bj][0], y1 = acc[ai][bj][m][1] * (rstd * qscale) * gv[bj][1];
;                         if (!isctx) {
;                             const int pos = bj == 0 ? (sp >> 6) : (sp & 63);
;                             const f32x4 c0 = *(const f32x4*)(ropec + pos * 16 + fbase), c1 = *(const f32x4*)(ropec + pos * 16 + fbase + 4);
;                             const f32x4 s0 = *(const f32x4*)(ropes + pos * 16 + fbase), s1 = *(const f32x4*)(ropes + pos * 16 + fbase + 4);
;                             f32x4 p0, p1;
; #pragma unroll
;                             for (int j = 0; j < 4; ++j) { p0[j] = xor32(y0[j], lowhalf); p1[j] = xor32(y1[j], lowhalf); }
;                             if (lowhalf) { y0 = y0 * c0 - p0 * s0; y1 = y1 * c1 - p1 * s1; }
;                             else         { y0 = p0 * s0 + y0 * c0; y1 = p1 * s1 + y1 * c1; }
;                         }
;                         u32x4 w; w.x = pk2(y0[0], y0[1]); w.y = pk2(y0[2], y0[3]); w.z = pk2(y1[0], y1[1]); w.w = pk2(y1[2], y1[3]);
;                         *(u32x4*)(dst + (size_t)row * pitch + hcol + 32 * bj + 8 * fq) = w;
.LBB0_285:
	v_cvt_pk_bf16_f32 v144, v192, v193
	v_cvt_pk_bf16_f32 v145, v190, v191
	v_cvt_pk_bf16_f32 v146, v194, v195
	v_cvt_pk_bf16_f32 v147, v186, v187
	global_store_dwordx4 v[188:189], v[144:147], off offset:64
	s_and_b64 vcc, exec, s[16:17]
	s_nop 0
	v_mul_f32_e32 v144, v49, v49
	v_mul_f32_e32 v145, v51, v51
	v_fmac_f32_e32 v144, v48, v48
	v_fmac_f32_e32 v145, v50, v50
	v_add_f32_e32 v144, v144, v145
	v_mul_f32_e32 v145, v41, v41
	v_mul_f32_e32 v146, v43, v43
	v_fmac_f32_e32 v145, v40, v40
	v_fmac_f32_e32 v146, v42, v42
	v_add_f32_e32 v145, v145, v146
	v_add_f32_e32 v144, v144, v145
	v_mul_f32_e32 v145, v37, v37
	v_mul_f32_e32 v146, v39, v39
	v_fmac_f32_e32 v145, v36, v36
	v_fmac_f32_e32 v146, v38, v38
	v_add_f32_e32 v145, v145, v146
	v_add_f32_e32 v144, v144, v145
	v_mul_f32_e32 v145, v29, v29
	v_mul_f32_e32 v146, v31, v31
	v_fmac_f32_e32 v145, v28, v28
	v_fmac_f32_e32 v146, v30, v30
	v_add_f32_e32 v145, v145, v146
	v_add_f32_e32 v144, v144, v145
	v_mov_b32_e32 v145, v144
	s_nop 1
	v_permlane16_swap_b32_e32 v144, v145
	v_add_f32_e32 v144, v144, v145
	v_mov_b32_e32 v145, v144
	s_nop 1
	v_permlane32_swap_b32_e32 v144, v145
	v_add_f32_e32 v144, v144, v145
	v_fmamk_f32 v144, v144, 0x3c800000, v200
	v_rsq_f32_e32 v144, v144
	s_nop 0
	v_mul_f32_e32 v186, v227, v144
	v_pk_mul_f32 v[144:145], v[48:49], v[186:187] op_sel_hi:[1,0]
	v_pk_mul_f32 v[146:147], v[50:51], v[186:187] op_sel_hi:[1,0]
	v_pk_mul_f32 v[192:193], v[140:141], v[144:145]
	v_pk_mul_f32 v[190:191], v[142:143], v[146:147]
	v_pk_mul_f32 v[144:145], v[40:41], v[186:187] op_sel_hi:[1,0]
	v_pk_mul_f32 v[146:147], v[42:43], v[186:187] op_sel_hi:[1,0]
	v_pk_mul_f32 v[196:197], v[136:137], v[144:145]
	v_pk_mul_f32 v[194:195], v[138:139], v[146:147]
	s_cbranch_vccnz .LBB0_291
	v_add_u32_e32 v144, s5, v223
	v_ashrrev_i32_e32 v144, 2, v144
	v_and_b32_e32 v144, -16, v144
	v_ashrrev_i32_e32 v145, 31, v144
	v_lshlrev_b64 v[148:149], 2, v[144:145]
	v_lshl_add_u64 v[150:151], v[172:173], 0, v[148:149]
	v_lshl_add_u64 v[156:157], v[174:175], 0, v[148:149]
	global_load_dwordx4 v[144:147], v[150:151], off offset:16
	global_load_dwordx4 v[152:155], v[150:151], off
	s_nop 0
	global_load_dwordx4 v[148:151], v[156:157], off offset:16
	s_nop 0
	global_load_dwordx4 v[156:159], v[156:157], off
	v_mov_b32_e32 v228, v192
	v_mov_b32_e32 v230, v196
	v_mov_b32_e32 v229, v193
	v_mov_b32_e32 v231, v197
	v_mov_b32_e32 v198, v190
	v_mov_b32_e32 v188, v194
	v_mov_b32_e32 v199, v191
	v_mov_b32_e32 v189, v195
	v_permlane32_swap_b32_e32 v228, v192
	v_permlane32_swap_b32_e32 v230, v196
	v_permlane32_swap_b32_e32 v229, v193
	v_permlane32_swap_b32_e32 v231, v197
	v_permlane32_swap_b32_e32 v198, v190
	v_permlane32_swap_b32_e32 v188, v194
	v_permlane32_swap_b32_e32 v199, v191
	v_permlane32_swap_b32_e32 v189, v195
	s_waitcnt vmcnt(1)
	s_waitcnt vmcnt(0)
	s_and_saveexec_b64 s[6:7], s[10:11]
	s_xor_b64 s[6:7], exec, s[6:7]
	v_pk_mul_f32 v[148:149], v[148:149], v[230:231]
	v_pk_mul_f32 v[156:157], v[156:157], v[228:229]
	v_pk_mul_f32 v[158:159], v[158:159], v[198:199]
	v_pk_mul_f32 v[150:151], v[150:151], v[188:189]
	v_pk_fma_f32 v[190:191], v[190:191], v[154:155], v[158:159]
	v_pk_fma_f32 v[192:193], v[192:193], v[152:153], v[156:157]
	v_pk_fma_f32 v[194:195], v[194:195], v[146:147], v[150:151]
	v_pk_fma_f32 v[196:197], v[196:197], v[144:145], v[148:149]
	s_andn2_saveexec_b64 s[6:7], s[6:7]
	v_pk_mul_f32 v[148:149], v[148:149], v[196:197]
	v_pk_mul_f32 v[156:157], v[156:157], v[192:193]
	v_pk_mul_f32 v[158:159], v[158:159], v[190:191]
	v_pk_mul_f32 v[150:151], v[150:151], v[194:195]
	v_pk_fma_f32 v[190:191], v[198:199], v[154:155], v[158:159] neg_lo:[0,0,1] neg_hi:[0,0,1]
	v_pk_fma_f32 v[192:193], v[228:229], v[152:153], v[156:157] neg_lo:[0,0,1] neg_hi:[0,0,1]
	v_pk_fma_f32 v[194:195], v[188:189], v[146:147], v[150:151] neg_lo:[0,0,1] neg_hi:[0,0,1]
	v_pk_fma_f32 v[196:197], v[230:231], v[144:145], v[148:149] neg_lo:[0,0,1] neg_hi:[0,0,1]
	s_or_b64 exec, exec, s[6:7]
.LBB0_291:
	v_add_u32_e32 v144, s26, v223
	v_ashrrev_i32_e32 v145, 31, v144
	v_lshlrev_b64 v[144:145], s27, v[144:145]
	v_lshl_add_u64 v[188:189], v[144:145], 1, v[184:185]
	v_cvt_pk_bf16_f32 v144, v192, v193
	v_cvt_pk_bf16_f32 v145, v190, v191
	v_cvt_pk_bf16_f32 v146, v196, v197
	v_cvt_pk_bf16_f32 v147, v194, v195
	global_store_dwordx4 v[188:189], v[144:147], off
	v_mov_b32_e32 v187, v186
	v_pk_mul_f32 v[148:149], v[36:37], v[186:187]
	v_mov_b32_e32 v144, v186
	v_mov_b32_e32 v145, v186
	v_pk_mul_f32 v[146:147], v[38:39], v[144:145]
	v_pk_mul_f32 v[144:145], v[30:31], v[144:145]
	v_pk_mul_f32 v[190:191], v[134:135], v[146:147]
	v_pk_mul_f32 v[146:147], v[28:29], v[186:187]
	v_pk_mul_f32 v[192:193], v[132:133], v[148:149]
	v_pk_mul_f32 v[186:187], v[130:131], v[144:145]
	s_and_b64 vcc, exec, s[16:17]
	v_pk_mul_f32 v[194:195], v[128:129], v[146:147]
	s_cbranch_vccnz .LBB0_297
	global_load_dwordx4 v[144:147], v[176:177], off offset:1040
	global_load_dwordx4 v[152:155], v[176:177], off offset:1024
	global_load_dwordx4 v[148:151], v[178:179], off offset:1040
	global_load_dwordx4 v[156:159], v[178:179], off offset:1024
	v_mov_b32_e32 v228, v192
	v_mov_b32_e32 v230, v194
	v_mov_b32_e32 v229, v193
	v_mov_b32_e32 v231, v195
	v_mov_b32_e32 v198, v190
	v_mov_b32_e32 v196, v186
	v_mov_b32_e32 v199, v191
	v_mov_b32_e32 v197, v187
	v_permlane32_swap_b32_e32 v228, v192
	v_permlane32_swap_b32_e32 v230, v194
	v_permlane32_swap_b32_e32 v229, v193
	v_permlane32_swap_b32_e32 v231, v195
	v_permlane32_swap_b32_e32 v198, v190
	v_permlane32_swap_b32_e32 v196, v186
	v_permlane32_swap_b32_e32 v199, v191
	v_permlane32_swap_b32_e32 v197, v187
	s_waitcnt vmcnt(1)
	s_waitcnt vmcnt(0)
	s_and_saveexec_b64 s[6:7], s[10:11]
	s_xor_b64 s[6:7], exec, s[6:7]
	v_pk_mul_f32 v[148:149], v[148:149], v[230:231]
	v_pk_mul_f32 v[156:157], v[156:157], v[228:229]
	v_pk_mul_f32 v[158:159], v[158:159], v[198:199]
	v_pk_mul_f32 v[150:151], v[150:151], v[196:197]
	v_pk_fma_f32 v[190:191], v[190:191], v[154:155], v[158:159]
	v_pk_fma_f32 v[192:193], v[192:193], v[152:153], v[156:157]
	v_pk_fma_f32 v[186:187], v[186:187], v[146:147], v[150:151]
	v_pk_fma_f32 v[194:195], v[194:195], v[144:145], v[148:149]
	s_andn2_saveexec_b64 s[6:7], s[6:7]
	v_pk_mul_f32 v[148:149], v[148:149], v[194:195]
	v_pk_mul_f32 v[156:157], v[156:157], v[192:193]
	v_pk_mul_f32 v[158:159], v[158:159], v[190:191]
	v_pk_mul_f32 v[150:151], v[150:151], v[186:187]
	v_pk_fma_f32 v[190:191], v[198:199], v[154:155], v[158:159] neg_lo:[0,0,1] neg_hi:[0,0,1]
	v_pk_fma_f32 v[192:193], v[228:229], v[152:153], v[156:157] neg_lo:[0,0,1] neg_hi:[0,0,1]
	v_pk_fma_f32 v[186:187], v[196:197], v[146:147], v[150:151] neg_lo:[0,0,1] neg_hi:[0,0,1]
	v_pk_fma_f32 v[194:195], v[230:231], v[144:145], v[148:149] neg_lo:[0,0,1] neg_hi:[0,0,1]
	s_or_b64 exec, exec, s[6:7]
; __device__ __forceinline__ unsigned pk2(float lo, float hi) { return pg8::cvt_pk_bf16(lo, hi); }
;     __device__ __forceinline__ void operator()(const f32x4 (&acc)[2][2][4][2], const pg8::Unit& u, int wr, int wc, int fr, int fq) const {
;     ...
;                         for (int n = 0; n < 2; ++n) { const f32x4 v = acc[ai][bj][m][n]; ss += (v[0] * v[0] + v[1] * v[1]) + (v[2] * v[2] + v[3] * v[3]); }
;                     ss = sum_fq(ss);
;                     const float rstd = __builtin_amdgcn_rsqf(ss * (1.0f / 64.0f) + EPS);
;                     const int sp = seq0 + rl;
; #pragma unroll
;                     for (int bj = 0; bj < 2; ++bj) {
;                         f32x4 y0 = acc[ai][bj][m][0] * (rstd * qscale) * gv[bj][0], y1 = acc[ai][bj][m][1] * (rstd * qscale) * gv[bj][1];
;                         if (!isctx) {
;                             const int pos = bj == 0 ? (sp >> 6) : (sp & 63);
;                             const f32x4 c0 = *(const f32x4*)(ropec + pos * 16 + fbase), c1 = *(const f32x4*)(ropec + pos * 16 + fbase + 4);
;                             const f32x4 s0 = *(const f32x4*)(ropes + pos * 16 + fbase), s1 = *(const f32x4*)(ropes + pos * 16 + fbase + 4);
;                             f32x4 p0, p1;
; #pragma unroll
;                             for (int j = 0; j < 4; ++j) { p0[j] = xor32(y0[j], lowhalf); p1[j] = xor32(y1[j], lowhalf); }
;                             if (lowhalf) { y0 = y0 * c0 - p0 * s0; y1 = y1 * c1 - p1 * s1; }
;                             else         { y0 = p0 * s0 + y0 * c0; y1 = p1 * s1 + y1 * c1; }
;                         }
;                         u32x4 w; w.x = pk2(y0[0], y0[1]); w.y = pk2(y0[2], y0[3]); w.z = pk2(y1[0], y1[1]); w.w = pk2(y1[2], y1[3]);
;                         *(u32x4*)(dst + (size_t)row * pitch + hcol + 32 * bj + 8 * fq) = w;
.LBB0_297:
	v_cvt_pk_bf16_f32 v144, v192, v193
	v_cvt_pk_bf16_f32 v145, v190, v191
	v_cvt_pk_bf16_f32 v146, v194, v195
	v_cvt_pk_bf16_f32 v147, v186, v187
	global_store_dwordx4 v[188:189], v[144:147], off offset:64
	s_and_b64 vcc, exec, s[16:17]
	s_nop 0
	v_mul_f32_e32 v144, v33, v33
	v_mul_f32_e32 v145, v35, v35
	v_fmac_f32_e32 v144, v32, v32
	v_fmac_f32_e32 v145, v34, v34
	v_add_f32_e32 v144, v144, v145
	v_mul_f32_e32 v145, v25, v25
	v_mul_f32_e32 v146, v27, v27
	v_fmac_f32_e32 v145, v24, v24
	v_fmac_f32_e32 v146, v26, v26
	v_add_f32_e32 v145, v145, v146
	v_add_f32_e32 v144, v144, v145
	v_mul_f32_e32 v145, v21, v21
	v_mul_f32_e32 v146, v23, v23
	v_fmac_f32_e32 v145, v20, v20
	v_fmac_f32_e32 v146, v22, v22
	v_add_f32_e32 v145, v145, v146
	v_add_f32_e32 v144, v144, v145
	v_mul_f32_e32 v145, v13, v13
	v_mul_f32_e32 v146, v15, v15
	v_fmac_f32_e32 v145, v12, v12
	v_fmac_f32_e32 v146, v14, v14
	v_add_f32_e32 v145, v145, v146
	v_add_f32_e32 v144, v144, v145
	v_mov_b32_e32 v145, v144
	s_nop 1
	v_permlane16_swap_b32_e32 v144, v145
	v_add_f32_e32 v144, v144, v145
	v_mov_b32_e32 v145, v144
	s_nop 1
	v_permlane32_swap_b32_e32 v144, v145
	v_add_f32_e32 v144, v144, v145
	v_fmamk_f32 v144, v144, 0x3c800000, v200
	v_rsq_f32_e32 v144, v144
	s_nop 0
	v_mul_f32_e32 v186, v227, v144
	v_pk_mul_f32 v[144:145], v[32:33], v[186:187] op_sel_hi:[1,0]
	v_pk_mul_f32 v[146:147], v[34:35], v[186:187] op_sel_hi:[1,0]
	v_pk_mul_f32 v[192:193], v[140:141], v[144:145]
	v_pk_mul_f32 v[190:191], v[142:143], v[146:147]
	v_pk_mul_f32 v[144:145], v[24:25], v[186:187] op_sel_hi:[1,0]
	v_pk_mul_f32 v[146:147], v[26:27], v[186:187] op_sel_hi:[1,0]
	v_pk_mul_f32 v[196:197], v[136:137], v[144:145]
	v_pk_mul_f32 v[194:195], v[138:139], v[146:147]
	s_cbranch_vccnz .LBB0_303
	v_add_u32_e32 v144, s5, v224
	v_ashrrev_i32_e32 v144, 2, v144
	v_and_b32_e32 v144, -16, v144
	v_ashrrev_i32_e32 v145, 31, v144
	v_lshlrev_b64 v[148:149], 2, v[144:145]
	v_lshl_add_u64 v[150:151], v[172:173], 0, v[148:149]
	v_lshl_add_u64 v[156:157], v[174:175], 0, v[148:149]
	global_load_dwordx4 v[144:147], v[150:151], off offset:16
	global_load_dwordx4 v[152:155], v[150:151], off
	s_nop 0
	global_load_dwordx4 v[148:151], v[156:157], off offset:16
	s_nop 0
	global_load_dwordx4 v[156:159], v[156:157], off
	v_mov_b32_e32 v228, v192
	v_mov_b32_e32 v230, v196
	v_mov_b32_e32 v229, v193
	v_mov_b32_e32 v231, v197
	v_mov_b32_e32 v198, v190
	v_mov_b32_e32 v188, v194
	v_mov_b32_e32 v199, v191
	v_mov_b32_e32 v189, v195
	v_permlane32_swap_b32_e32 v228, v192
	v_permlane32_swap_b32_e32 v230, v196
	v_permlane32_swap_b32_e32 v229, v193
	v_permlane32_swap_b32_e32 v231, v197
	v_permlane32_swap_b32_e32 v198, v190
	v_permlane32_swap_b32_e32 v188, v194
	v_permlane32_swap_b32_e32 v199, v191
	v_permlane32_swap_b32_e32 v189, v195
	s_waitcnt vmcnt(1)
	s_waitcnt vmcnt(0)
	s_and_saveexec_b64 s[6:7], s[10:11]
	s_xor_b64 s[6:7], exec, s[6:7]
	v_pk_mul_f32 v[148:149], v[148:149], v[230:231]
	v_pk_mul_f32 v[156:157], v[156:157], v[228:229]
	v_pk_mul_f32 v[158:159], v[158:159], v[198:199]
	v_pk_mul_f32 v[150:151], v[150:151], v[188:189]
	v_pk_fma_f32 v[190:191], v[190:191], v[154:155], v[158:159]
	v_pk_fma_f32 v[192:193], v[192:193], v[152:153], v[156:157]
	v_pk_fma_f32 v[194:195], v[194:195], v[146:147], v[150:151]
	v_pk_fma_f32 v[196:197], v[196:197], v[144:145], v[148:149]
	s_andn2_saveexec_b64 s[6:7], s[6:7]
	v_pk_mul_f32 v[148:149], v[148:149], v[196:197]
	v_pk_mul_f32 v[156:157], v[156:157], v[192:193]
	v_pk_mul_f32 v[158:159], v[158:159], v[190:191]
	v_pk_mul_f32 v[150:151], v[150:151], v[194:195]
	v_pk_fma_f32 v[190:191], v[198:199], v[154:155], v[158:159] neg_lo:[0,0,1] neg_hi:[0,0,1]
	v_pk_fma_f32 v[192:193], v[228:229], v[152:153], v[156:157] neg_lo:[0,0,1] neg_hi:[0,0,1]
	v_pk_fma_f32 v[194:195], v[188:189], v[146:147], v[150:151] neg_lo:[0,0,1] neg_hi:[0,0,1]
	v_pk_fma_f32 v[196:197], v[230:231], v[144:145], v[148:149] neg_lo:[0,0,1] neg_hi:[0,0,1]
	s_or_b64 exec, exec, s[6:7]
.LBB0_303:
	v_add_u32_e32 v144, s26, v224
	v_ashrrev_i32_e32 v145, 31, v144
	v_lshlrev_b64 v[144:145], s27, v[144:145]
	v_lshl_add_u64 v[188:189], v[144:145], 1, v[184:185]
	v_cvt_pk_bf16_f32 v144, v192, v193
	v_cvt_pk_bf16_f32 v145, v190, v191
	v_cvt_pk_bf16_f32 v146, v196, v197
	v_cvt_pk_bf16_f32 v147, v194, v195
	global_store_dwordx4 v[188:189], v[144:147], off
	v_mov_b32_e32 v187, v186
	v_pk_mul_f32 v[148:149], v[20:21], v[186:187]
	v_mov_b32_e32 v144, v186
	v_mov_b32_e32 v145, v186
	v_pk_mul_f32 v[146:147], v[22:23], v[144:145]
	v_pk_mul_f32 v[144:145], v[14:15], v[144:145]
	v_pk_mul_f32 v[190:191], v[134:135], v[146:147]
	v_pk_mul_f32 v[146:147], v[12:13], v[186:187]
	v_pk_mul_f32 v[192:193], v[132:133], v[148:149]
	v_pk_mul_f32 v[186:187], v[130:131], v[144:145]
	s_and_b64 vcc, exec, s[16:17]
	v_pk_mul_f32 v[194:195], v[128:129], v[146:147]
	s_cbranch_vccnz .LBB0_309
	global_load_dwordx4 v[144:147], v[176:177], off offset:2064
	global_load_dwordx4 v[152:155], v[176:177], off offset:2048
	global_load_dwordx4 v[148:151], v[178:179], off offset:2064
	global_load_dwordx4 v[156:159], v[178:179], off offset:2048
	v_mov_b32_e32 v228, v192
	v_mov_b32_e32 v230, v194
	v_mov_b32_e32 v229, v193
	v_mov_b32_e32 v231, v195
	v_mov_b32_e32 v198, v190
	v_mov_b32_e32 v196, v186
	v_mov_b32_e32 v199, v191
	v_mov_b32_e32 v197, v187
	v_permlane32_swap_b32_e32 v228, v192
	v_permlane32_swap_b32_e32 v230, v194
	v_permlane32_swap_b32_e32 v229, v193
	v_permlane32_swap_b32_e32 v231, v195
	v_permlane32_swap_b32_e32 v198, v190
	v_permlane32_swap_b32_e32 v196, v186
	v_permlane32_swap_b32_e32 v199, v191
	v_permlane32_swap_b32_e32 v197, v187
	s_waitcnt vmcnt(1)
	s_waitcnt vmcnt(0)
	s_and_saveexec_b64 s[6:7], s[10:11]
	s_xor_b64 s[6:7], exec, s[6:7]
	v_pk_mul_f32 v[148:149], v[148:149], v[230:231]
	v_pk_mul_f32 v[156:157], v[156:157], v[228:229]
	v_pk_mul_f32 v[158:159], v[158:159], v[198:199]
	v_pk_mul_f32 v[150:151], v[150:151], v[196:197]
	v_pk_fma_f32 v[190:191], v[190:191], v[154:155], v[158:159]
	v_pk_fma_f32 v[192:193], v[192:193], v[152:153], v[156:157]
	v_pk_fma_f32 v[186:187], v[186:187], v[146:147], v[150:151]
	v_pk_fma_f32 v[194:195], v[194:195], v[144:145], v[148:149]
	s_andn2_saveexec_b64 s[6:7], s[6:7]
	v_pk_mul_f32 v[148:149], v[148:149], v[194:195]
	v_pk_mul_f32 v[156:157], v[156:157], v[192:193]
	v_pk_mul_f32 v[158:159], v[158:159], v[190:191]
	v_pk_mul_f32 v[150:151], v[150:151], v[186:187]
	v_pk_fma_f32 v[190:191], v[198:199], v[154:155], v[158:159] neg_lo:[0,0,1] neg_hi:[0,0,1]
	v_pk_fma_f32 v[192:193], v[228:229], v[152:153], v[156:157] neg_lo:[0,0,1] neg_hi:[0,0,1]
	v_pk_fma_f32 v[186:187], v[196:197], v[146:147], v[150:151] neg_lo:[0,0,1] neg_hi:[0,0,1]
	v_pk_fma_f32 v[194:195], v[230:231], v[144:145], v[148:149] neg_lo:[0,0,1] neg_hi:[0,0,1]
	s_or_b64 exec, exec, s[6:7]
; __device__ __forceinline__ unsigned pk2(float lo, float hi) { return pg8::cvt_pk_bf16(lo, hi); }
;     __device__ __forceinline__ void operator()(const f32x4 (&acc)[2][2][4][2], const pg8::Unit& u, int wr, int wc, int fr, int fq) const {
;     ...
;                         for (int n = 0; n < 2; ++n) { const f32x4 v = acc[ai][bj][m][n]; ss += (v[0] * v[0] + v[1] * v[1]) + (v[2] * v[2] + v[3] * v[3]); }
;                     ss = sum_fq(ss);
;                     const float rstd = __builtin_amdgcn_rsqf(ss * (1.0f / 64.0f) + EPS);
;                     const int sp = seq0 + rl;
; #pragma unroll
;                     for (int bj = 0; bj < 2; ++bj) {
;                         f32x4 y0 = acc[ai][bj][m][0] * (rstd * qscale) * gv[bj][0], y1 = acc[ai][bj][m][1] * (rstd * qscale) * gv[bj][1];
;                         if (!isctx) {
;                             const int pos = bj == 0 ? (sp >> 6) : (sp & 63);
;                             const f32x4 c0 = *(const f32x4*)(ropec + pos * 16 + fbase), c1 = *(const f32x4*)(ropec + pos * 16 + fbase + 4);
;                             const f32x4 s0 = *(const f32x4*)(ropes + pos * 16 + fbase), s1 = *(const f32x4*)(ropes + pos * 16 + fbase + 4);
;                             f32x4 p0, p1;
; #pragma unroll
;                             for (int j = 0; j < 4; ++j) { p0[j] = xor32(y0[j], lowhalf); p1[j] = xor32(y1[j], lowhalf); }
;                             if (lowhalf) { y0 = y0 * c0 - p0 * s0; y1 = y1 * c1 - p1 * s1; }
;                             else         { y0 = p0 * s0 + y0 * c0; y1 = p1 * s1 + y1 * c1; }
;                         }
;                         u32x4 w; w.x = pk2(y0[0], y0[1]); w.y = pk2(y0[2], y0[3]); w.z = pk2(y1[0], y1[1]); w.w = pk2(y1[2], y1[3]);
;                         *(u32x4*)(dst + (size_t)row * pitch + hcol + 32 * bj + 8 * fq) = w;
.LBB0_309:
	v_cvt_pk_bf16_f32 v144, v192, v193
	v_cvt_pk_bf16_f32 v145, v190, v191
	v_cvt_pk_bf16_f32 v146, v194, v195
	v_cvt_pk_bf16_f32 v147, v186, v187
	global_store_dwordx4 v[188:189], v[144:147], off offset:64
	s_and_b64 vcc, exec, s[16:17]
	s_nop 0
	v_mul_f32_e32 v144, v17, v17
	v_mul_f32_e32 v145, v19, v19
	v_fmac_f32_e32 v144, v16, v16
	v_fmac_f32_e32 v145, v18, v18
	v_add_f32_e32 v144, v144, v145
	v_mul_f32_e32 v145, v9, v9
	v_mul_f32_e32 v146, v11, v11
	v_fmac_f32_e32 v145, v8, v8
	v_fmac_f32_e32 v146, v10, v10
	v_add_f32_e32 v145, v145, v146
	v_add_f32_e32 v144, v144, v145
	v_mul_f32_e32 v145, v5, v5
	v_mul_f32_e32 v146, v7, v7
	v_fmac_f32_e32 v145, v4, v4
	v_fmac_f32_e32 v146, v6, v6
	v_add_f32_e32 v145, v145, v146
	v_add_f32_e32 v144, v144, v145
	v_mul_f32_e32 v145, v1, v1
	v_mul_f32_e32 v146, v3, v3
	v_fmac_f32_e32 v145, v0, v0
	v_fmac_f32_e32 v146, v2, v2
	v_add_f32_e32 v145, v145, v146
	v_add_f32_e32 v144, v144, v145
	v_mov_b32_e32 v145, v144
	s_nop 1
	v_permlane16_swap_b32_e32 v144, v145
	v_add_f32_e32 v144, v144, v145
	v_mov_b32_e32 v145, v144
	s_nop 1
	v_permlane32_swap_b32_e32 v144, v145
	v_add_f32_e32 v144, v144, v145
	v_fmamk_f32 v144, v144, 0x3c800000, v200
	v_rsq_f32_e32 v144, v144
	s_nop 0
	v_mul_f32_e32 v152, v227, v144
	v_pk_mul_f32 v[144:145], v[16:17], v[152:153] op_sel_hi:[1,0]
	v_pk_mul_f32 v[146:147], v[18:19], v[152:153] op_sel_hi:[1,0]
	v_pk_mul_f32 v[156:157], v[140:141], v[144:145]
	v_pk_mul_f32 v[154:155], v[142:143], v[146:147]
	v_pk_mul_f32 v[140:141], v[8:9], v[152:153] op_sel_hi:[1,0]
	v_pk_mul_f32 v[142:143], v[10:11], v[152:153] op_sel_hi:[1,0]
	v_pk_mul_f32 v[186:187], v[136:137], v[140:141]
	v_pk_mul_f32 v[158:159], v[138:139], v[142:143]
	s_cbranch_vccnz .LBB0_315
	v_add_u32_e32 v136, s5, v225
	v_ashrrev_i32_e32 v136, 2, v136
	v_and_b32_e32 v136, -16, v136
	v_ashrrev_i32_e32 v137, 31, v136
	v_lshlrev_b64 v[140:141], 2, v[136:137]
	v_lshl_add_u64 v[142:143], v[172:173], 0, v[140:141]
	v_lshl_add_u64 v[148:149], v[174:175], 0, v[140:141]
	global_load_dwordx4 v[136:139], v[142:143], off offset:16
	global_load_dwordx4 v[144:147], v[142:143], off
	s_nop 0
	global_load_dwordx4 v[140:143], v[148:149], off offset:16
	s_nop 0
	global_load_dwordx4 v[148:151], v[148:149], off
	v_mov_b32_e32 v192, v156
	v_mov_b32_e32 v194, v186
	v_mov_b32_e32 v193, v157
	v_mov_b32_e32 v195, v187
	v_mov_b32_e32 v190, v154
	v_mov_b32_e32 v188, v158
	v_mov_b32_e32 v191, v155
	v_mov_b32_e32 v189, v159
	v_permlane32_swap_b32_e32 v192, v156
	v_permlane32_swap_b32_e32 v194, v186
	v_permlane32_swap_b32_e32 v193, v157
	v_permlane32_swap_b32_e32 v195, v187
	v_permlane32_swap_b32_e32 v190, v154
	v_permlane32_swap_b32_e32 v188, v158
	v_permlane32_swap_b32_e32 v191, v155
	v_permlane32_swap_b32_e32 v189, v159
	s_waitcnt vmcnt(1)
	s_waitcnt vmcnt(0)
	s_and_saveexec_b64 s[6:7], s[10:11]
	s_xor_b64 s[6:7], exec, s[6:7]
	v_pk_mul_f32 v[140:141], v[140:141], v[194:195]
	v_pk_mul_f32 v[148:149], v[148:149], v[192:193]
	v_pk_mul_f32 v[150:151], v[150:151], v[190:191]
	v_pk_mul_f32 v[142:143], v[142:143], v[188:189]
	v_pk_fma_f32 v[154:155], v[154:155], v[146:147], v[150:151]
	v_pk_fma_f32 v[156:157], v[156:157], v[144:145], v[148:149]
	v_pk_fma_f32 v[158:159], v[158:159], v[138:139], v[142:143]
	v_pk_fma_f32 v[186:187], v[186:187], v[136:137], v[140:141]
	s_andn2_saveexec_b64 s[6:7], s[6:7]
	v_pk_mul_f32 v[140:141], v[140:141], v[186:187]
	v_pk_mul_f32 v[148:149], v[148:149], v[156:157]
	v_pk_mul_f32 v[150:151], v[150:151], v[154:155]
	v_pk_mul_f32 v[142:143], v[142:143], v[158:159]
	v_pk_fma_f32 v[154:155], v[190:191], v[146:147], v[150:151] neg_lo:[0,0,1] neg_hi:[0,0,1]
	v_pk_fma_f32 v[156:157], v[192:193], v[144:145], v[148:149] neg_lo:[0,0,1] neg_hi:[0,0,1]
	v_pk_fma_f32 v[158:159], v[188:189], v[138:139], v[142:143] neg_lo:[0,0,1] neg_hi:[0,0,1]
	v_pk_fma_f32 v[186:187], v[194:195], v[136:137], v[140:141] neg_lo:[0,0,1] neg_hi:[0,0,1]
	s_or_b64 exec, exec, s[6:7]
.LBB0_315:
	v_add_u32_e32 v136, s26, v225
	v_ashrrev_i32_e32 v137, 31, v136
	v_lshlrev_b64 v[136:137], s27, v[136:137]
	v_lshl_add_u64 v[144:145], v[136:137], 1, v[184:185]
	v_cvt_pk_bf16_f32 v136, v156, v157
	v_cvt_pk_bf16_f32 v137, v154, v155
	v_mov_b32_e32 v153, v152
	v_cvt_pk_bf16_f32 v138, v186, v187
	v_cvt_pk_bf16_f32 v139, v158, v159
	global_store_dwordx4 v[144:145], v[136:139], off
	v_pk_mul_f32 v[140:141], v[4:5], v[152:153]
	s_and_b64 vcc, exec, s[16:17]
	v_mov_b32_e32 v136, v152
	v_mov_b32_e32 v137, v152
	v_pk_mul_f32 v[138:139], v[6:7], v[136:137]
	v_pk_mul_f32 v[148:149], v[132:133], v[140:141]
	v_pk_mul_f32 v[146:147], v[134:135], v[138:139]
	v_pk_mul_f32 v[132:133], v[2:3], v[136:137]
	v_pk_mul_f32 v[134:135], v[0:1], v[152:153]
	v_pk_mul_f32 v[150:151], v[130:131], v[132:133]
	v_pk_mul_f32 v[152:153], v[128:129], v[134:135]
	s_cbranch_vccnz .LBB0_321
	global_load_dwordx4 v[128:131], v[176:177], off offset:3088
	global_load_dwordx4 v[136:139], v[176:177], off offset:3072
	global_load_dwordx4 v[132:135], v[178:179], off offset:3088
	global_load_dwordx4 v[140:143], v[178:179], off offset:3072
	v_mov_b32_e32 v158, v148
	v_mov_b32_e32 v184, v152
	v_mov_b32_e32 v159, v149
	v_mov_b32_e32 v185, v153
	v_mov_b32_e32 v156, v146
	v_mov_b32_e32 v154, v150
	v_mov_b32_e32 v157, v147
	v_mov_b32_e32 v155, v151
	v_permlane32_swap_b32_e32 v158, v148
	v_permlane32_swap_b32_e32 v184, v152
	v_permlane32_swap_b32_e32 v159, v149
	v_permlane32_swap_b32_e32 v185, v153
	v_permlane32_swap_b32_e32 v156, v146
	v_permlane32_swap_b32_e32 v154, v150
	v_permlane32_swap_b32_e32 v157, v147
	v_permlane32_swap_b32_e32 v155, v151
	s_waitcnt vmcnt(1)
	s_waitcnt vmcnt(0)
	s_and_saveexec_b64 s[6:7], s[10:11]
	s_xor_b64 s[6:7], exec, s[6:7]
	v_pk_mul_f32 v[132:133], v[132:133], v[184:185]
	v_pk_mul_f32 v[140:141], v[140:141], v[158:159]
	v_pk_mul_f32 v[142:143], v[142:143], v[156:157]
	v_pk_mul_f32 v[134:135], v[134:135], v[154:155]
	v_pk_fma_f32 v[146:147], v[146:147], v[138:139], v[142:143]
	v_pk_fma_f32 v[148:149], v[148:149], v[136:137], v[140:141]
	v_pk_fma_f32 v[150:151], v[150:151], v[130:131], v[134:135]
	v_pk_fma_f32 v[152:153], v[152:153], v[128:129], v[132:133]
	s_andn2_saveexec_b64 s[6:7], s[6:7]
	v_pk_mul_f32 v[132:133], v[132:133], v[152:153]
	v_pk_mul_f32 v[140:141], v[140:141], v[148:149]
	v_pk_mul_f32 v[142:143], v[142:143], v[146:147]
	v_pk_mul_f32 v[134:135], v[134:135], v[150:151]
	v_pk_fma_f32 v[146:147], v[156:157], v[138:139], v[142:143] neg_lo:[0,0,1] neg_hi:[0,0,1]
	v_pk_fma_f32 v[148:149], v[158:159], v[136:137], v[140:141] neg_lo:[0,0,1] neg_hi:[0,0,1]
	v_pk_fma_f32 v[150:151], v[154:155], v[130:131], v[134:135] neg_lo:[0,0,1] neg_hi:[0,0,1]
	v_pk_fma_f32 v[152:153], v[184:185], v[128:129], v[132:133] neg_lo:[0,0,1] neg_hi:[0,0,1]
	s_or_b64 exec, exec, s[6:7]
